# P4 layer 1: main loop stops at 11 full rounds, rows 32512..32767 done as 110 64-row sub-tiles instead of a 44-tile 12th round
# speedup vs baseline: 1.0037x; 1.0037x over previous
.LBB0_1087:
	s_mul_hi_i32 s2, s49, 0x2e8ba2e9
	s_lshr_b32 s3, s2, 31
	s_ashr_i32 s2, s2, 6
	s_add_i32 s2, s2, s3
	s_lshl_b32 s3, s2, 4
	s_sub_i32 s4, s7, s3
	s_min_i32 s4, s4, 16
	s_abs_i32 s5, s4
	v_cvt_f32_u32_e32 v3, s5
	s_sub_i32 s20, 0, s5
	s_mulk_i32 s2, 0xfea0
	s_add_i32 s2, s2, s49
	v_rcp_iflag_f32_e32 v3, v3
	s_abs_i32 s19, s2
	s_xor_b32 s18, s2, s4
	s_ashr_i32 s18, s18, 31
	v_mul_f32_e32 v3, 0x4f7ffffe, v3
	v_cvt_u32_f32_e32 v3, v3
	v_mov_b32_e32 v1, v222
	v_mov_b32_e32 v9, v211
	v_readfirstlane_b32 s21, v3
	s_mul_i32 s20, s20, s21
	s_mul_hi_u32 s20, s21, s20
	s_add_i32 s21, s21, s20
	s_mul_hi_u32 s20, s19, s21
	s_mul_i32 s21, s20, s5
	s_sub_i32 s19, s19, s21
	s_add_i32 s21, s20, 1
	s_sub_i32 s22, s19, s5
	s_cmp_ge_u32 s19, s5
	s_cselect_b32 s20, s21, s20
	s_cselect_b32 s19, s22, s19
	s_add_i32 s21, s20, 1
	s_cmp_ge_u32 s19, s5
	s_cselect_b32 s5, s21, s20
	s_xor_b32 s5, s5, s18
	s_sub_i32 s18, s5, s18
	s_mul_i32 s4, s18, s4
	s_sub_i32 s2, s2, s4
	s_add_i32 s2, s2, s3
	s_mul_i32 s28, s2, 0xfe
	s_add_i32 s28, s28, -1
	s_cmp_eq_u32 s6, 0x8000
	s_cselect_b32 s2, 0xb00, s58
	s_nop 0
	v_writelane_b32 v255, s2, 50
	v_lshrrev_b32_e32 v202, 3, v222
	v_lshrrev_b32_e32 v203, 4, v222
	v_xor_b32_e32 v203, v203, v222
	v_and_b32_e32 v203, 7, v203
	v_lshlrev_b32_e32 v210, 4, v203
	v_mov_b32_e32 v200, s46
	v_mov_b32_e32 v201, s47
	v_add_u32_e32 v204, s28, v202
	v_mov_b32_e32 v205, 0
	v_cmp_gt_u32_e32 vcc, s6, v204
	v_lshlrev_b64 v[196:197], 11, v[204:205]
	v_lshl_add_u64 v[196:197], s[64:65], 0, v[196:197]
	v_cndmask_b32_e32 v196, v200, v196, vcc
	v_cndmask_b32_e32 v197, v201, v197, vcc
	v_lshl_add_u64 v[218:219], v[196:197], 0, v[210:211]
	v_add_u32_e32 v204, 64, v204
	v_cmp_gt_u32_e32 vcc, s6, v204
	v_lshlrev_b64 v[196:197], 11, v[204:205]
	v_lshl_add_u64 v[196:197], s[64:65], 0, v[196:197]
	v_cndmask_b32_e32 v196, v200, v196, vcc
	v_cndmask_b32_e32 v197, v201, v197, vcc
	v_lshl_add_u64 v[220:221], v[196:197], 0, v[210:211]
	v_add_u32_e32 v204, 64, v204
	v_cmp_gt_u32_e32 vcc, s6, v204
	v_lshlrev_b64 v[196:197], 11, v[204:205]
	v_lshl_add_u64 v[196:197], s[64:65], 0, v[196:197]
	v_cndmask_b32_e32 v196, v200, v196, vcc
	v_cndmask_b32_e32 v197, v201, v197, vcc
	v_lshl_add_u64 v[224:225], v[196:197], 0, v[210:211]
	v_add_u32_e32 v204, 64, v204
	v_cmp_gt_u32_e32 vcc, s6, v204
	v_lshlrev_b64 v[196:197], 11, v[204:205]
	v_lshl_add_u64 v[196:197], s[64:65], 0, v[196:197]
	v_cndmask_b32_e32 v196, v200, v196, vcc
	v_cndmask_b32_e32 v197, v201, v197, vcc
	v_lshl_add_u64 v[226:227], v[196:197], 0, v[210:211]
	s_lshl_b32 s2, s18, 19
	s_add_u32 s2, s55, s2
	s_addc_u32 s3, s48, 0
	v_lshlrev_b32_e32 v196, 11, v202
	v_add_u32_e32 v196, v196, v210
	v_mov_b32_e32 v197, 0
	v_lshl_add_u64 v[228:229], v[196:197], 0, s[2:3]
	v_readfirstlane_b32 s19, v222
	s_nop 3
	s_lshr_b32 s29, s19, 8
	s_lshr_b32 s19, s19, 6
	s_lshl_b32 s19, s19, 10
	s_barrier
	s_mov_b32 s20, 0
	s_mov_b32 s21, 0
	s_mov_b32 s23, 0
	s_mov_b32 m0, s19
	v_lshl_add_u64 v[196:197], v[218:219], 0, s[20:21]
	global_load_lds_dwordx4 v[196:197], off
	s_add_i32 m0, s19, 0x2000
	v_lshl_add_u64 v[198:199], v[220:221], 0, s[20:21]
	global_load_lds_dwordx4 v[198:199], off
	s_add_i32 m0, s19, 0x4000
	v_lshl_add_u64 v[196:197], v[224:225], 0, s[20:21]
	global_load_lds_dwordx4 v[196:197], off
	s_add_i32 m0, s19, 0x6000
	v_lshl_add_u64 v[198:199], v[226:227], 0, s[20:21]
	global_load_lds_dwordx4 v[198:199], off
	s_add_i32 m0, s19, 0x8000
	v_lshl_add_u64 v[196:197], v[228:229], 0, s[20:21]
	global_load_lds_dwordx4 v[196:197], off
	s_add_u32 s22, s20, 0x20000
	s_add_i32 m0, s19, 0xa000
	v_lshl_add_u64 v[198:199], v[228:229], 0, s[22:23]
	global_load_lds_dwordx4 v[198:199], off
	s_add_u32 s22, s20, 0x40000
	s_add_i32 m0, s19, 0xc000
	v_lshl_add_u64 v[196:197], v[228:229], 0, s[22:23]
	global_load_lds_dwordx4 v[196:197], off
	s_add_u32 s22, s20, 0x60000
	s_add_i32 m0, s19, 0xe000
	v_lshl_add_u64 v[198:199], v[228:229], 0, s[22:23]
	global_load_lds_dwordx4 v[198:199], off
	s_waitcnt vmcnt(0)

.Lp4_skew1:
	s_nop 7
	s_nop 1
	s_mov_b32 s94, s18
	s_mov_b32 s34, s28
	v_bfe_u32 v201, v222, 6, 2
	v_bfe_u32 v202, v222, 4, 2
	v_lshlrev_b32_e32 v203, 2, v202
	v_lshl_or_b32 v203, v201, 5, v203
	s_lshl_b32 s4, s94, 7
	v_or_b32_e32 v204, s4, v203
	v_lshlrev_b32_e32 v205, 2, v204
	global_load_dwordx4 v[130:133], v205, s[10:11]
	global_load_dwordx4 v[134:137], v205, s[12:13]
	global_load_dwordx4 v[138:141], v205, s[14:15]
	global_load_dwordx4 v[142:145], v205, s[10:11] offset:64
	global_load_dwordx4 v[146:149], v205, s[12:13] offset:64
	global_load_dwordx4 v[150:153], v205, s[14:15] offset:64
	s_add_i32 s2, s49, s95
	v_readlane_b32 s3, v255, 50
	s_nop 0
	s_cmp_lt_i32 s2, s3
	s_cselect_b32 s35, 1, 0
	s_cselect_b32 s49, s2, s49
	s_mul_hi_i32 s2, s49, 0x2e8ba2e9
	s_lshr_b32 s3, s2, 31
	s_ashr_i32 s2, s2, 6
	s_add_i32 s2, s2, s3
	s_lshl_b32 s3, s2, 4
	s_sub_i32 s4, s7, s3
	s_min_i32 s4, s4, 16
	s_abs_i32 s5, s4
	v_cvt_f32_u32_e32 v199, s5
	s_sub_i32 s20, 0, s5
	s_mulk_i32 s2, 0xfea0
	s_add_i32 s2, s2, s49
	v_rcp_iflag_f32_e32 v199, v199
	s_abs_i32 s19, s2
	s_xor_b32 s18, s2, s4
	s_ashr_i32 s18, s18, 31
	v_mul_f32_e32 v199, 0x4f7ffffe, v199
	v_cvt_u32_f32_e32 v199, v199
	s_nop 1
	v_readfirstlane_b32 s21, v199
	s_mul_i32 s20, s20, s21
	s_mul_hi_u32 s20, s21, s20
	s_add_i32 s21, s21, s20
	s_mul_hi_u32 s20, s19, s21
	s_mul_i32 s21, s20, s5
	s_sub_i32 s19, s19, s21
	s_add_i32 s21, s20, 1
	s_sub_i32 s22, s19, s5
	s_cmp_ge_u32 s19, s5
	s_cselect_b32 s20, s21, s20
	s_cselect_b32 s19, s22, s19
	s_add_i32 s21, s20, 1
	s_cmp_ge_u32 s19, s5
	s_cselect_b32 s5, s21, s20
	s_xor_b32 s5, s5, s18
	s_sub_i32 s18, s5, s18
	s_mul_i32 s4, s18, s4
	s_sub_i32 s2, s2, s4
	s_add_i32 s2, s2, s3
	s_mul_i32 s28, s2, 0xfe
	s_add_i32 s28, s28, -1
	v_lshrrev_b32_e32 v202, 3, v222
	v_lshrrev_b32_e32 v203, 4, v222
	v_xor_b32_e32 v203, v203, v222
	v_and_b32_e32 v203, 7, v203
	v_lshlrev_b32_e32 v210, 4, v203
	v_mov_b32_e32 v200, s46
	v_mov_b32_e32 v201, s47
	v_add_u32_e32 v204, s28, v202
	v_mov_b32_e32 v205, 0
	v_cmp_gt_u32_e32 vcc, s6, v204
	v_lshlrev_b64 v[196:197], 11, v[204:205]
	v_lshl_add_u64 v[196:197], s[64:65], 0, v[196:197]
	v_cndmask_b32_e32 v196, v200, v196, vcc
	v_cndmask_b32_e32 v197, v201, v197, vcc
	v_lshl_add_u64 v[218:219], v[196:197], 0, v[210:211]
	v_add_u32_e32 v204, 64, v204
	v_cmp_gt_u32_e32 vcc, s6, v204
	v_lshlrev_b64 v[196:197], 11, v[204:205]
	v_lshl_add_u64 v[196:197], s[64:65], 0, v[196:197]
	v_cndmask_b32_e32 v196, v200, v196, vcc
	v_cndmask_b32_e32 v197, v201, v197, vcc
	v_lshl_add_u64 v[220:221], v[196:197], 0, v[210:211]
	v_add_u32_e32 v204, 64, v204
	v_cmp_gt_u32_e32 vcc, s6, v204
	v_lshlrev_b64 v[196:197], 11, v[204:205]
	v_lshl_add_u64 v[196:197], s[64:65], 0, v[196:197]
	v_cndmask_b32_e32 v196, v200, v196, vcc
	v_cndmask_b32_e32 v197, v201, v197, vcc
	v_lshl_add_u64 v[224:225], v[196:197], 0, v[210:211]
	v_add_u32_e32 v204, 64, v204
	v_cmp_gt_u32_e32 vcc, s6, v204
	v_lshlrev_b64 v[196:197], 11, v[204:205]
	v_lshl_add_u64 v[196:197], s[64:65], 0, v[196:197]
	v_cndmask_b32_e32 v196, v200, v196, vcc
	v_cndmask_b32_e32 v197, v201, v197, vcc
	v_lshl_add_u64 v[226:227], v[196:197], 0, v[210:211]
	s_lshl_b32 s2, s18, 19
	s_add_u32 s2, s55, s2
	s_addc_u32 s3, s48, 0
	v_lshlrev_b32_e32 v196, 11, v202
	v_add_u32_e32 v196, v196, v210
	v_mov_b32_e32 v197, 0
	v_lshl_add_u64 v[228:229], v[196:197], 0, s[2:3]
	v_readfirstlane_b32 s19, v222
	s_nop 3
	s_lshr_b32 s29, s19, 8
	s_lshr_b32 s19, s19, 6
	s_lshl_b32 s19, s19, 10
	s_mov_b32 s20, 0
	s_mov_b32 s21, 0
	s_mov_b32 s23, 0
	s_mov_b32 m0, s19
	v_lshl_add_u64 v[196:197], v[218:219], 0, s[20:21]
	global_load_lds_dwordx4 v[196:197], off
	s_add_i32 m0, s19, 0x2000
	v_lshl_add_u64 v[198:199], v[220:221], 0, s[20:21]
	global_load_lds_dwordx4 v[198:199], off
	s_add_i32 m0, s19, 0x4000
	v_lshl_add_u64 v[196:197], v[224:225], 0, s[20:21]
	global_load_lds_dwordx4 v[196:197], off
	s_add_i32 m0, s19, 0x6000
	v_lshl_add_u64 v[198:199], v[226:227], 0, s[20:21]
	global_load_lds_dwordx4 v[198:199], off
	s_add_i32 m0, s19, 0x8000
	v_lshl_add_u64 v[196:197], v[228:229], 0, s[20:21]
	global_load_lds_dwordx4 v[196:197], off
	s_add_u32 s22, s20, 0x20000
	s_add_i32 m0, s19, 0xa000
	v_lshl_add_u64 v[198:199], v[228:229], 0, s[22:23]
	global_load_lds_dwordx4 v[198:199], off
	s_add_u32 s22, s20, 0x40000
	s_add_i32 m0, s19, 0xc000
	v_lshl_add_u64 v[196:197], v[228:229], 0, s[22:23]
	global_load_lds_dwordx4 v[196:197], off
	s_add_u32 s22, s20, 0x60000
	s_add_i32 m0, s19, 0xe000
	v_lshl_add_u64 v[198:199], v[228:229], 0, s[22:23]
	global_load_lds_dwordx4 v[198:199], off
	v_and_b32_e32 v200, 15, v222
	v_lshrrev_b32_e32 v201, 8, v222
	v_lshl_or_b32 v200, v201, 7, v200
	v_bfe_u32 v201, v222, 6, 2
	v_bfe_u32 v202, v222, 4, 2
	v_lshlrev_b32_e32 v203, 2, v202
	v_lshl_or_b32 v203, v201, 5, v203
	s_lshl_b32 s4, s94, 7
	v_or_b32_e32 v204, s4, v203
	v_lshlrev_b32_e32 v205, 2, v204
	v_lshlrev_b32_e32 v207, 1, v204
	v_mul_u32_u24_e32 v206, 0x110, v200
	v_lshl_add_u32 v206, v203, 1, v206
	v_add_u32_e32 v206, 0x10000, v206
	v_cvt_pk_f16_f32 v170, v126, v127
	v_cvt_pk_f16_f32 v171, v128, v129
	v_cvt_pk_f16_f32 v172, v118, v119
	v_cvt_pk_f16_f32 v173, v120, v121
	ds_write2_b64 v206, v[170:171], v[172:173] offset1:4
	v_cvt_pk_f16_f32 v174, v110, v111
	v_cvt_pk_f16_f32 v175, v112, v113
	v_cvt_pk_f16_f32 v176, v102, v103
	v_cvt_pk_f16_f32 v177, v104, v105
	v_add_u32_e32 v178, 0x1100, v206
	ds_write2_b64 v178, v[174:175], v[176:177] offset1:4
	v_cvt_pk_f16_f32 v170, v94, v95
	v_cvt_pk_f16_f32 v171, v96, v97
	v_cvt_pk_f16_f32 v172, v86, v87
	v_cvt_pk_f16_f32 v173, v88, v89
	v_add_u32_e32 v178, 0x2200, v206
	ds_write2_b64 v178, v[170:171], v[172:173] offset1:4
	v_cvt_pk_f16_f32 v174, v78, v79
	v_cvt_pk_f16_f32 v175, v80, v81
	v_cvt_pk_f16_f32 v176, v70, v71
	v_cvt_pk_f16_f32 v177, v72, v73
	v_add_u32_e32 v178, 0x3300, v206
	ds_write2_b64 v178, v[174:175], v[176:177] offset1:4
	v_cvt_pk_f16_f32 v170, v62, v63
	v_cvt_pk_f16_f32 v171, v64, v65
	v_cvt_pk_f16_f32 v172, v54, v55
	v_cvt_pk_f16_f32 v173, v56, v57
	v_add_u32_e32 v178, 0x4400, v206
	ds_write2_b64 v178, v[170:171], v[172:173] offset1:4
	v_cvt_pk_f16_f32 v174, v46, v47
	v_cvt_pk_f16_f32 v175, v48, v49
	v_cvt_pk_f16_f32 v176, v38, v39
	v_cvt_pk_f16_f32 v177, v40, v41
	v_add_u32_e32 v178, 0x5500, v206
	ds_write2_b64 v178, v[174:175], v[176:177] offset1:4
	v_cvt_pk_f16_f32 v170, v30, v31
	v_cvt_pk_f16_f32 v171, v32, v33
	v_cvt_pk_f16_f32 v172, v22, v23
	v_cvt_pk_f16_f32 v173, v24, v25
	v_add_u32_e32 v178, 0x6600, v206
	ds_write2_b64 v178, v[170:171], v[172:173] offset1:4
	v_cvt_pk_f16_f32 v174, v14, v15
	v_cvt_pk_f16_f32 v175, v16, v17
	v_cvt_pk_f16_f32 v176, v6, v7
	v_cvt_pk_f16_f32 v177, v8, v9
	v_add_u32_e32 v178, 0x7700, v206
	ds_write2_b64 v178, v[174:175], v[176:177] offset1:4
	v_add_u32_e32 v201, 0xfffffef0, v206
	s_waitcnt lgkmcnt(0)
	s_barrier
	ds_read2_b64 v[154:157], v201 offset1:4
	ds_read2_b64 v[158:161], v201 offset0:68 offset1:72
	s_waitcnt vmcnt(8)
	v_add_u32_e32 v179, 0x1100, v201
	ds_read2_b64 v[162:165], v179 offset1:4
	ds_read2_b64 v[166:169], v179 offset0:68 offset1:72
	v_add_u32_e32 v180, 0, v200
	v_add_u32_e32 v181, s34, v180
	v_add_u32_e32 v182, -1, v180
	v_cmp_gt_u32_e32 vcc, 0xfe, v182
	v_cmp_gt_i32_e64 s[2:3], s6, v181
	v_cmp_gt_i32_e64 s[4:5], s68, v181
	v_mad_u32_u24 v183, v181, s52, v207
	s_and_b64 s[2:3], vcc, s[2:3]
	v_cndmask_b32_e64 v184, v216, v217, s[4:5]
	v_and_b32_e32 v185, v184, v181
	v_cmp_eq_u32_e32 vcc, 0, v185
	s_nop 1
	v_cndmask_b32_e64 v186, -1, 0, vcc
	v_cmp_eq_u32_e32 vcc, v185, v184
	s_nop 1
	v_cndmask_b32_e64 v188, -1, 0, vcc
	s_and_saveexec_b64 s[4:5], s[2:3]
	s_waitcnt lgkmcnt(2)
	v_pk_mul_f32 v[126:127], v[126:127], v[134:135]
	v_pk_mul_f32 v[128:129], v[128:129], v[136:137]
	v_and_b32_e32 v154, v186, v154
	v_and_b32_e32 v155, v186, v155
	v_and_b32_e32 v158, v188, v158
	v_and_b32_e32 v159, v188, v159
	v_fma_mix_f32 v126, v130, v154, v126 op_sel:[0,0,0] op_sel_hi:[0,1,0]
	v_fma_mix_f32 v127, v131, v154, v127 op_sel:[0,1,0] op_sel_hi:[0,1,0]
	v_fma_mix_f32 v128, v132, v155, v128 op_sel:[0,0,0] op_sel_hi:[0,1,0]
	v_fma_mix_f32 v129, v133, v155, v129 op_sel:[0,1,0] op_sel_hi:[0,1,0]
	v_fma_mix_f32 v126, v138, v158, v126 op_sel:[0,0,0] op_sel_hi:[0,1,0]
	v_fma_mix_f32 v127, v139, v158, v127 op_sel:[0,1,0] op_sel_hi:[0,1,0]
	v_fma_mix_f32 v128, v140, v159, v128 op_sel:[0,0,0] op_sel_hi:[0,1,0]
	v_fma_mix_f32 v129, v141, v159, v129 op_sel:[0,1,0] op_sel_hi:[0,1,0]
	v_mul_f32_e32 v190, 0xbfb8aa3b, v126
	v_mul_f32_e32 v191, 0xbfb8aa3b, v127
	v_mul_f32_e32 v192, 0xbfb8aa3b, v128
	v_mul_f32_e32 v193, 0xbfb8aa3b, v129
	v_exp_f32_e32 v190, v190
	v_exp_f32_e32 v191, v191
	v_exp_f32_e32 v192, v192
	v_exp_f32_e32 v193, v193
	v_add_f32_e32 v190, 1.0, v190
	v_add_f32_e32 v191, 1.0, v191
	v_add_f32_e32 v192, 1.0, v192
	v_add_f32_e32 v193, 1.0, v193
	v_rcp_f32_e32 v190, v190
	v_rcp_f32_e32 v191, v191
	v_rcp_f32_e32 v192, v192
	v_rcp_f32_e32 v193, v193
	s_nop 0
	v_pk_mul_f32 v[126:127], v[126:127], v[190:191]
	v_pk_mul_f32 v[128:129], v[128:129], v[192:193]
	v_pk_mul_f32 v[126:127], v[122:123], v[126:127]
	v_pk_mul_f32 v[128:129], v[124:125], v[128:129]
	v_cvt_pk_f16_f32 v126, v126, v127
	v_cvt_pk_f16_f32 v127, v128, v129
	global_store_dwordx2 v183, v[126:127], s[96:97]
	v_pk_mul_f32 v[118:119], v[118:119], v[146:147]
	v_pk_mul_f32 v[120:121], v[120:121], v[148:149]
	v_and_b32_e32 v156, v186, v156
	v_and_b32_e32 v157, v186, v157
	v_and_b32_e32 v160, v188, v160
	v_and_b32_e32 v161, v188, v161
	v_fma_mix_f32 v118, v142, v156, v118 op_sel:[0,0,0] op_sel_hi:[0,1,0]
	v_fma_mix_f32 v119, v143, v156, v119 op_sel:[0,1,0] op_sel_hi:[0,1,0]
	v_fma_mix_f32 v120, v144, v157, v120 op_sel:[0,0,0] op_sel_hi:[0,1,0]
	v_fma_mix_f32 v121, v145, v157, v121 op_sel:[0,1,0] op_sel_hi:[0,1,0]
	v_fma_mix_f32 v118, v150, v160, v118 op_sel:[0,0,0] op_sel_hi:[0,1,0]
	v_fma_mix_f32 v119, v151, v160, v119 op_sel:[0,1,0] op_sel_hi:[0,1,0]
	v_fma_mix_f32 v120, v152, v161, v120 op_sel:[0,0,0] op_sel_hi:[0,1,0]
	v_fma_mix_f32 v121, v153, v161, v121 op_sel:[0,1,0] op_sel_hi:[0,1,0]
	v_mul_f32_e32 v190, 0xbfb8aa3b, v118
	v_mul_f32_e32 v191, 0xbfb8aa3b, v119
	v_mul_f32_e32 v192, 0xbfb8aa3b, v120
	v_mul_f32_e32 v193, 0xbfb8aa3b, v121
	v_exp_f32_e32 v190, v190
	v_exp_f32_e32 v191, v191
	v_exp_f32_e32 v192, v192
	v_exp_f32_e32 v193, v193
	v_add_f32_e32 v190, 1.0, v190
	v_add_f32_e32 v191, 1.0, v191
	v_add_f32_e32 v192, 1.0, v192
	v_add_f32_e32 v193, 1.0, v193
	v_rcp_f32_e32 v190, v190
	v_rcp_f32_e32 v191, v191
	v_rcp_f32_e32 v192, v192
	v_rcp_f32_e32 v193, v193
	s_nop 0
	v_pk_mul_f32 v[118:119], v[118:119], v[190:191]
	v_pk_mul_f32 v[120:121], v[120:121], v[192:193]
	v_pk_mul_f32 v[118:119], v[114:115], v[118:119]
	v_pk_mul_f32 v[120:121], v[116:117], v[120:121]
	v_cvt_pk_f16_f32 v118, v118, v119
	v_cvt_pk_f16_f32 v119, v120, v121
	global_store_dwordx2 v183, v[118:119], s[96:97] offset:32
	s_mov_b64 exec, s[4:5]
	v_add_u32_e32 v179, 0x2200, v201
	ds_read2_b64 v[154:157], v179 offset1:4
	ds_read2_b64 v[158:161], v179 offset0:68 offset1:72
	v_add_u32_e32 v180, 16, v200
	v_add_u32_e32 v181, s34, v180
	v_add_u32_e32 v182, -1, v180
	v_cmp_gt_u32_e32 vcc, 0xfe, v182
	v_cmp_gt_i32_e64 s[2:3], s6, v181
	v_cmp_gt_i32_e64 s[4:5], s68, v181
	v_mad_u32_u24 v183, v181, s52, v207
	s_and_b64 s[2:3], vcc, s[2:3]
	v_cndmask_b32_e64 v184, v216, v217, s[4:5]
	v_and_b32_e32 v185, v184, v181
	v_cmp_eq_u32_e32 vcc, 0, v185
	s_nop 1
	v_cndmask_b32_e64 v186, -1, 0, vcc
	v_cmp_eq_u32_e32 vcc, v185, v184
	s_nop 1
	v_cndmask_b32_e64 v188, -1, 0, vcc
	s_and_saveexec_b64 s[4:5], s[2:3]
	s_waitcnt lgkmcnt(2)
	v_pk_mul_f32 v[110:111], v[110:111], v[134:135]
	v_pk_mul_f32 v[112:113], v[112:113], v[136:137]
	v_and_b32_e32 v162, v186, v162
	v_and_b32_e32 v163, v186, v163
	v_and_b32_e32 v166, v188, v166
	v_and_b32_e32 v167, v188, v167
	v_fma_mix_f32 v110, v130, v162, v110 op_sel:[0,0,0] op_sel_hi:[0,1,0]
	v_fma_mix_f32 v111, v131, v162, v111 op_sel:[0,1,0] op_sel_hi:[0,1,0]
	v_fma_mix_f32 v112, v132, v163, v112 op_sel:[0,0,0] op_sel_hi:[0,1,0]
	v_fma_mix_f32 v113, v133, v163, v113 op_sel:[0,1,0] op_sel_hi:[0,1,0]
	v_fma_mix_f32 v110, v138, v166, v110 op_sel:[0,0,0] op_sel_hi:[0,1,0]
	v_fma_mix_f32 v111, v139, v166, v111 op_sel:[0,1,0] op_sel_hi:[0,1,0]
	v_fma_mix_f32 v112, v140, v167, v112 op_sel:[0,0,0] op_sel_hi:[0,1,0]
	v_fma_mix_f32 v113, v141, v167, v113 op_sel:[0,1,0] op_sel_hi:[0,1,0]
	v_mul_f32_e32 v190, 0xbfb8aa3b, v110
	v_mul_f32_e32 v191, 0xbfb8aa3b, v111
	v_mul_f32_e32 v192, 0xbfb8aa3b, v112
	v_mul_f32_e32 v193, 0xbfb8aa3b, v113
	v_exp_f32_e32 v190, v190
	v_exp_f32_e32 v191, v191
	v_exp_f32_e32 v192, v192
	v_exp_f32_e32 v193, v193
	v_add_f32_e32 v190, 1.0, v190
	v_add_f32_e32 v191, 1.0, v191
	v_add_f32_e32 v192, 1.0, v192
	v_add_f32_e32 v193, 1.0, v193
	v_rcp_f32_e32 v190, v190
	v_rcp_f32_e32 v191, v191
	v_rcp_f32_e32 v192, v192
	v_rcp_f32_e32 v193, v193
	s_nop 0
	v_pk_mul_f32 v[110:111], v[110:111], v[190:191]
	v_pk_mul_f32 v[112:113], v[112:113], v[192:193]
	v_pk_mul_f32 v[110:111], v[106:107], v[110:111]
	v_pk_mul_f32 v[112:113], v[108:109], v[112:113]
	v_cvt_pk_f16_f32 v110, v110, v111
	v_cvt_pk_f16_f32 v111, v112, v113
	global_store_dwordx2 v183, v[110:111], s[96:97]
	v_pk_mul_f32 v[102:103], v[102:103], v[146:147]
	v_pk_mul_f32 v[104:105], v[104:105], v[148:149]
	v_and_b32_e32 v164, v186, v164
	v_and_b32_e32 v165, v186, v165
	v_and_b32_e32 v168, v188, v168
	v_and_b32_e32 v169, v188, v169
	v_fma_mix_f32 v102, v142, v164, v102 op_sel:[0,0,0] op_sel_hi:[0,1,0]
	v_fma_mix_f32 v103, v143, v164, v103 op_sel:[0,1,0] op_sel_hi:[0,1,0]
	v_fma_mix_f32 v104, v144, v165, v104 op_sel:[0,0,0] op_sel_hi:[0,1,0]
	v_fma_mix_f32 v105, v145, v165, v105 op_sel:[0,1,0] op_sel_hi:[0,1,0]
	v_fma_mix_f32 v102, v150, v168, v102 op_sel:[0,0,0] op_sel_hi:[0,1,0]
	v_fma_mix_f32 v103, v151, v168, v103 op_sel:[0,1,0] op_sel_hi:[0,1,0]
	v_fma_mix_f32 v104, v152, v169, v104 op_sel:[0,0,0] op_sel_hi:[0,1,0]
	v_fma_mix_f32 v105, v153, v169, v105 op_sel:[0,1,0] op_sel_hi:[0,1,0]
	v_mul_f32_e32 v190, 0xbfb8aa3b, v102
	v_mul_f32_e32 v191, 0xbfb8aa3b, v103
	v_mul_f32_e32 v192, 0xbfb8aa3b, v104
	v_mul_f32_e32 v193, 0xbfb8aa3b, v105
	v_exp_f32_e32 v190, v190
	v_exp_f32_e32 v191, v191
	v_exp_f32_e32 v192, v192
	v_exp_f32_e32 v193, v193
	v_add_f32_e32 v190, 1.0, v190
	v_add_f32_e32 v191, 1.0, v191
	v_add_f32_e32 v192, 1.0, v192
	v_add_f32_e32 v193, 1.0, v193
	v_rcp_f32_e32 v190, v190
	v_rcp_f32_e32 v191, v191
	v_rcp_f32_e32 v192, v192
	v_rcp_f32_e32 v193, v193
	s_nop 0
	v_pk_mul_f32 v[102:103], v[102:103], v[190:191]
	v_pk_mul_f32 v[104:105], v[104:105], v[192:193]
	v_pk_mul_f32 v[102:103], v[98:99], v[102:103]
	v_pk_mul_f32 v[104:105], v[100:101], v[104:105]
	v_cvt_pk_f16_f32 v102, v102, v103
	v_cvt_pk_f16_f32 v103, v104, v105
	global_store_dwordx2 v183, v[102:103], s[96:97] offset:32
	s_mov_b64 exec, s[4:5]
	v_add_u32_e32 v179, 0x3300, v201
	ds_read2_b64 v[162:165], v179 offset1:4
	ds_read2_b64 v[166:169], v179 offset0:68 offset1:72
	v_add_u32_e32 v180, 32, v200
	v_add_u32_e32 v181, s34, v180
	v_add_u32_e32 v182, -1, v180
	v_cmp_gt_u32_e32 vcc, 0xfe, v182
	v_cmp_gt_i32_e64 s[2:3], s6, v181
	v_cmp_gt_i32_e64 s[4:5], s68, v181
	v_mad_u32_u24 v183, v181, s52, v207
	s_and_b64 s[2:3], vcc, s[2:3]
	v_cndmask_b32_e64 v184, v216, v217, s[4:5]
	v_and_b32_e32 v185, v184, v181
	v_cmp_eq_u32_e32 vcc, 0, v185
	s_nop 1
	v_cndmask_b32_e64 v186, -1, 0, vcc
	v_cmp_eq_u32_e32 vcc, v185, v184
	s_nop 1
	v_cndmask_b32_e64 v188, -1, 0, vcc
	s_and_saveexec_b64 s[4:5], s[2:3]
	s_waitcnt lgkmcnt(2)
	v_pk_mul_f32 v[94:95], v[94:95], v[134:135]
	v_pk_mul_f32 v[96:97], v[96:97], v[136:137]
	v_and_b32_e32 v154, v186, v154
	v_and_b32_e32 v155, v186, v155
	v_and_b32_e32 v158, v188, v158
	v_and_b32_e32 v159, v188, v159
	v_fma_mix_f32 v94, v130, v154, v94 op_sel:[0,0,0] op_sel_hi:[0,1,0]
	v_fma_mix_f32 v95, v131, v154, v95 op_sel:[0,1,0] op_sel_hi:[0,1,0]
	v_fma_mix_f32 v96, v132, v155, v96 op_sel:[0,0,0] op_sel_hi:[0,1,0]
	v_fma_mix_f32 v97, v133, v155, v97 op_sel:[0,1,0] op_sel_hi:[0,1,0]
	v_fma_mix_f32 v94, v138, v158, v94 op_sel:[0,0,0] op_sel_hi:[0,1,0]
	v_fma_mix_f32 v95, v139, v158, v95 op_sel:[0,1,0] op_sel_hi:[0,1,0]
	v_fma_mix_f32 v96, v140, v159, v96 op_sel:[0,0,0] op_sel_hi:[0,1,0]
	v_fma_mix_f32 v97, v141, v159, v97 op_sel:[0,1,0] op_sel_hi:[0,1,0]
	v_mul_f32_e32 v190, 0xbfb8aa3b, v94
	v_mul_f32_e32 v191, 0xbfb8aa3b, v95
	v_mul_f32_e32 v192, 0xbfb8aa3b, v96
	v_mul_f32_e32 v193, 0xbfb8aa3b, v97
	v_exp_f32_e32 v190, v190
	v_exp_f32_e32 v191, v191
	v_exp_f32_e32 v192, v192
	v_exp_f32_e32 v193, v193
	v_add_f32_e32 v190, 1.0, v190
	v_add_f32_e32 v191, 1.0, v191
	v_add_f32_e32 v192, 1.0, v192
	v_add_f32_e32 v193, 1.0, v193
	v_rcp_f32_e32 v190, v190
	v_rcp_f32_e32 v191, v191
	v_rcp_f32_e32 v192, v192
	v_rcp_f32_e32 v193, v193
	s_nop 0
	v_pk_mul_f32 v[94:95], v[94:95], v[190:191]
	v_pk_mul_f32 v[96:97], v[96:97], v[192:193]
	v_pk_mul_f32 v[94:95], v[90:91], v[94:95]
	v_pk_mul_f32 v[96:97], v[92:93], v[96:97]
	v_cvt_pk_f16_f32 v94, v94, v95
	v_cvt_pk_f16_f32 v95, v96, v97
	global_store_dwordx2 v183, v[94:95], s[96:97]
	v_pk_mul_f32 v[86:87], v[86:87], v[146:147]
	v_pk_mul_f32 v[88:89], v[88:89], v[148:149]
	v_and_b32_e32 v156, v186, v156
	v_and_b32_e32 v157, v186, v157
	v_and_b32_e32 v160, v188, v160
	v_and_b32_e32 v161, v188, v161
	v_fma_mix_f32 v86, v142, v156, v86 op_sel:[0,0,0] op_sel_hi:[0,1,0]
	v_fma_mix_f32 v87, v143, v156, v87 op_sel:[0,1,0] op_sel_hi:[0,1,0]
	v_fma_mix_f32 v88, v144, v157, v88 op_sel:[0,0,0] op_sel_hi:[0,1,0]
	v_fma_mix_f32 v89, v145, v157, v89 op_sel:[0,1,0] op_sel_hi:[0,1,0]
	v_fma_mix_f32 v86, v150, v160, v86 op_sel:[0,0,0] op_sel_hi:[0,1,0]
	v_fma_mix_f32 v87, v151, v160, v87 op_sel:[0,1,0] op_sel_hi:[0,1,0]
	v_fma_mix_f32 v88, v152, v161, v88 op_sel:[0,0,0] op_sel_hi:[0,1,0]
	v_fma_mix_f32 v89, v153, v161, v89 op_sel:[0,1,0] op_sel_hi:[0,1,0]
	v_mul_f32_e32 v190, 0xbfb8aa3b, v86
	v_mul_f32_e32 v191, 0xbfb8aa3b, v87
	v_mul_f32_e32 v192, 0xbfb8aa3b, v88
	v_mul_f32_e32 v193, 0xbfb8aa3b, v89
	v_exp_f32_e32 v190, v190
	v_exp_f32_e32 v191, v191
	v_exp_f32_e32 v192, v192
	v_exp_f32_e32 v193, v193
	v_add_f32_e32 v190, 1.0, v190
	v_add_f32_e32 v191, 1.0, v191
	v_add_f32_e32 v192, 1.0, v192
	v_add_f32_e32 v193, 1.0, v193
	v_rcp_f32_e32 v190, v190
	v_rcp_f32_e32 v191, v191
	v_rcp_f32_e32 v192, v192
	v_rcp_f32_e32 v193, v193
	s_nop 0
	v_pk_mul_f32 v[86:87], v[86:87], v[190:191]
	v_pk_mul_f32 v[88:89], v[88:89], v[192:193]
	v_pk_mul_f32 v[86:87], v[82:83], v[86:87]
	v_pk_mul_f32 v[88:89], v[84:85], v[88:89]
	v_cvt_pk_f16_f32 v86, v86, v87
	v_cvt_pk_f16_f32 v87, v88, v89
	global_store_dwordx2 v183, v[86:87], s[96:97] offset:32
	s_mov_b64 exec, s[4:5]
	v_add_u32_e32 v179, 0x4400, v201
	ds_read2_b64 v[154:157], v179 offset1:4
	ds_read2_b64 v[158:161], v179 offset0:68 offset1:72
	v_add_u32_e32 v180, 48, v200
	v_add_u32_e32 v181, s34, v180
	v_add_u32_e32 v182, -1, v180
	v_cmp_gt_u32_e32 vcc, 0xfe, v182
	v_cmp_gt_i32_e64 s[2:3], s6, v181
	v_cmp_gt_i32_e64 s[4:5], s68, v181
	v_mad_u32_u24 v183, v181, s52, v207
	s_and_b64 s[2:3], vcc, s[2:3]
	v_cndmask_b32_e64 v184, v216, v217, s[4:5]
	v_and_b32_e32 v185, v184, v181
	v_cmp_eq_u32_e32 vcc, 0, v185
	s_nop 1
	v_cndmask_b32_e64 v186, -1, 0, vcc
	v_cmp_eq_u32_e32 vcc, v185, v184
	s_nop 1
	v_cndmask_b32_e64 v188, -1, 0, vcc
	s_and_saveexec_b64 s[4:5], s[2:3]
	s_waitcnt lgkmcnt(2)
	v_pk_mul_f32 v[78:79], v[78:79], v[134:135]
	v_pk_mul_f32 v[80:81], v[80:81], v[136:137]
	v_and_b32_e32 v162, v186, v162
	v_and_b32_e32 v163, v186, v163
	v_and_b32_e32 v166, v188, v166
	v_and_b32_e32 v167, v188, v167
	v_fma_mix_f32 v78, v130, v162, v78 op_sel:[0,0,0] op_sel_hi:[0,1,0]
	v_fma_mix_f32 v79, v131, v162, v79 op_sel:[0,1,0] op_sel_hi:[0,1,0]
	v_fma_mix_f32 v80, v132, v163, v80 op_sel:[0,0,0] op_sel_hi:[0,1,0]
	v_fma_mix_f32 v81, v133, v163, v81 op_sel:[0,1,0] op_sel_hi:[0,1,0]
	v_fma_mix_f32 v78, v138, v166, v78 op_sel:[0,0,0] op_sel_hi:[0,1,0]
	v_fma_mix_f32 v79, v139, v166, v79 op_sel:[0,1,0] op_sel_hi:[0,1,0]
	v_fma_mix_f32 v80, v140, v167, v80 op_sel:[0,0,0] op_sel_hi:[0,1,0]
	v_fma_mix_f32 v81, v141, v167, v81 op_sel:[0,1,0] op_sel_hi:[0,1,0]
	v_mul_f32_e32 v190, 0xbfb8aa3b, v78
	v_mul_f32_e32 v191, 0xbfb8aa3b, v79
	v_mul_f32_e32 v192, 0xbfb8aa3b, v80
	v_mul_f32_e32 v193, 0xbfb8aa3b, v81
	v_exp_f32_e32 v190, v190
	v_exp_f32_e32 v191, v191
	v_exp_f32_e32 v192, v192
	v_exp_f32_e32 v193, v193
	v_add_f32_e32 v190, 1.0, v190
	v_add_f32_e32 v191, 1.0, v191
	v_add_f32_e32 v192, 1.0, v192
	v_add_f32_e32 v193, 1.0, v193
	v_rcp_f32_e32 v190, v190
	v_rcp_f32_e32 v191, v191
	v_rcp_f32_e32 v192, v192
	v_rcp_f32_e32 v193, v193
	s_nop 0
	v_pk_mul_f32 v[78:79], v[78:79], v[190:191]
	v_pk_mul_f32 v[80:81], v[80:81], v[192:193]
	v_pk_mul_f32 v[78:79], v[74:75], v[78:79]
	v_pk_mul_f32 v[80:81], v[76:77], v[80:81]
	v_cvt_pk_f16_f32 v78, v78, v79
	v_cvt_pk_f16_f32 v79, v80, v81
	global_store_dwordx2 v183, v[78:79], s[96:97]
	v_pk_mul_f32 v[70:71], v[70:71], v[146:147]
	v_pk_mul_f32 v[72:73], v[72:73], v[148:149]
	v_and_b32_e32 v164, v186, v164
	v_and_b32_e32 v165, v186, v165
	v_and_b32_e32 v168, v188, v168
	v_and_b32_e32 v169, v188, v169
	v_fma_mix_f32 v70, v142, v164, v70 op_sel:[0,0,0] op_sel_hi:[0,1,0]
	v_fma_mix_f32 v71, v143, v164, v71 op_sel:[0,1,0] op_sel_hi:[0,1,0]
	v_fma_mix_f32 v72, v144, v165, v72 op_sel:[0,0,0] op_sel_hi:[0,1,0]
	v_fma_mix_f32 v73, v145, v165, v73 op_sel:[0,1,0] op_sel_hi:[0,1,0]
	v_fma_mix_f32 v70, v150, v168, v70 op_sel:[0,0,0] op_sel_hi:[0,1,0]
	v_fma_mix_f32 v71, v151, v168, v71 op_sel:[0,1,0] op_sel_hi:[0,1,0]
	v_fma_mix_f32 v72, v152, v169, v72 op_sel:[0,0,0] op_sel_hi:[0,1,0]
	v_fma_mix_f32 v73, v153, v169, v73 op_sel:[0,1,0] op_sel_hi:[0,1,0]
	v_mul_f32_e32 v190, 0xbfb8aa3b, v70
	v_mul_f32_e32 v191, 0xbfb8aa3b, v71
	v_mul_f32_e32 v192, 0xbfb8aa3b, v72
	v_mul_f32_e32 v193, 0xbfb8aa3b, v73
	v_exp_f32_e32 v190, v190
	v_exp_f32_e32 v191, v191
	v_exp_f32_e32 v192, v192
	v_exp_f32_e32 v193, v193
	v_add_f32_e32 v190, 1.0, v190
	v_add_f32_e32 v191, 1.0, v191
	v_add_f32_e32 v192, 1.0, v192
	v_add_f32_e32 v193, 1.0, v193
	v_rcp_f32_e32 v190, v190
	v_rcp_f32_e32 v191, v191
	v_rcp_f32_e32 v192, v192
	v_rcp_f32_e32 v193, v193
	s_nop 0
	v_pk_mul_f32 v[70:71], v[70:71], v[190:191]
	v_pk_mul_f32 v[72:73], v[72:73], v[192:193]
	v_pk_mul_f32 v[70:71], v[66:67], v[70:71]
	v_pk_mul_f32 v[72:73], v[68:69], v[72:73]
	v_cvt_pk_f16_f32 v70, v70, v71
	v_cvt_pk_f16_f32 v71, v72, v73
	global_store_dwordx2 v183, v[70:71], s[96:97] offset:32
	s_mov_b64 exec, s[4:5]
	v_add_u32_e32 v179, 0x5500, v201
	ds_read2_b64 v[162:165], v179 offset1:4
	ds_read2_b64 v[166:169], v179 offset0:68 offset1:72
	v_add_u32_e32 v180, 64, v200
	v_add_u32_e32 v181, s34, v180
	v_add_u32_e32 v182, -1, v180
	v_cmp_gt_u32_e32 vcc, 0xfe, v182
	v_cmp_gt_i32_e64 s[2:3], s6, v181
	v_cmp_gt_i32_e64 s[4:5], s68, v181
	v_mad_u32_u24 v183, v181, s52, v207
	s_and_b64 s[2:3], vcc, s[2:3]
	v_cndmask_b32_e64 v184, v216, v217, s[4:5]
	v_and_b32_e32 v185, v184, v181
	v_cmp_eq_u32_e32 vcc, 0, v185
	s_nop 1
	v_cndmask_b32_e64 v186, -1, 0, vcc
	v_cmp_eq_u32_e32 vcc, v185, v184
	s_nop 1
	v_cndmask_b32_e64 v188, -1, 0, vcc
	s_and_saveexec_b64 s[4:5], s[2:3]
	s_waitcnt lgkmcnt(2)
	v_pk_mul_f32 v[62:63], v[62:63], v[134:135]
	v_pk_mul_f32 v[64:65], v[64:65], v[136:137]
	v_and_b32_e32 v154, v186, v154
	v_and_b32_e32 v155, v186, v155
	v_and_b32_e32 v158, v188, v158
	v_and_b32_e32 v159, v188, v159
	v_fma_mix_f32 v62, v130, v154, v62 op_sel:[0,0,0] op_sel_hi:[0,1,0]
	v_fma_mix_f32 v63, v131, v154, v63 op_sel:[0,1,0] op_sel_hi:[0,1,0]
	v_fma_mix_f32 v64, v132, v155, v64 op_sel:[0,0,0] op_sel_hi:[0,1,0]
	v_fma_mix_f32 v65, v133, v155, v65 op_sel:[0,1,0] op_sel_hi:[0,1,0]
	v_fma_mix_f32 v62, v138, v158, v62 op_sel:[0,0,0] op_sel_hi:[0,1,0]
	v_fma_mix_f32 v63, v139, v158, v63 op_sel:[0,1,0] op_sel_hi:[0,1,0]
	v_fma_mix_f32 v64, v140, v159, v64 op_sel:[0,0,0] op_sel_hi:[0,1,0]
	v_fma_mix_f32 v65, v141, v159, v65 op_sel:[0,1,0] op_sel_hi:[0,1,0]
	v_mul_f32_e32 v190, 0xbfb8aa3b, v62
	v_mul_f32_e32 v191, 0xbfb8aa3b, v63
	v_mul_f32_e32 v192, 0xbfb8aa3b, v64
	v_mul_f32_e32 v193, 0xbfb8aa3b, v65
	v_exp_f32_e32 v190, v190
	v_exp_f32_e32 v191, v191
	v_exp_f32_e32 v192, v192
	v_exp_f32_e32 v193, v193
	v_add_f32_e32 v190, 1.0, v190
	v_add_f32_e32 v191, 1.0, v191
	v_add_f32_e32 v192, 1.0, v192
	v_add_f32_e32 v193, 1.0, v193
	v_rcp_f32_e32 v190, v190
	v_rcp_f32_e32 v191, v191
	v_rcp_f32_e32 v192, v192
	v_rcp_f32_e32 v193, v193
	s_nop 0
	v_pk_mul_f32 v[62:63], v[62:63], v[190:191]
	v_pk_mul_f32 v[64:65], v[64:65], v[192:193]
	v_pk_mul_f32 v[62:63], v[58:59], v[62:63]
	v_pk_mul_f32 v[64:65], v[60:61], v[64:65]
	v_cvt_pk_f16_f32 v62, v62, v63
	v_cvt_pk_f16_f32 v63, v64, v65
	global_store_dwordx2 v183, v[62:63], s[96:97]
	v_pk_mul_f32 v[54:55], v[54:55], v[146:147]
	v_pk_mul_f32 v[56:57], v[56:57], v[148:149]
	v_and_b32_e32 v156, v186, v156
	v_and_b32_e32 v157, v186, v157
	v_and_b32_e32 v160, v188, v160
	v_and_b32_e32 v161, v188, v161
	v_fma_mix_f32 v54, v142, v156, v54 op_sel:[0,0,0] op_sel_hi:[0,1,0]
	v_fma_mix_f32 v55, v143, v156, v55 op_sel:[0,1,0] op_sel_hi:[0,1,0]
	v_fma_mix_f32 v56, v144, v157, v56 op_sel:[0,0,0] op_sel_hi:[0,1,0]
	v_fma_mix_f32 v57, v145, v157, v57 op_sel:[0,1,0] op_sel_hi:[0,1,0]
	v_fma_mix_f32 v54, v150, v160, v54 op_sel:[0,0,0] op_sel_hi:[0,1,0]
	v_fma_mix_f32 v55, v151, v160, v55 op_sel:[0,1,0] op_sel_hi:[0,1,0]
	v_fma_mix_f32 v56, v152, v161, v56 op_sel:[0,0,0] op_sel_hi:[0,1,0]
	v_fma_mix_f32 v57, v153, v161, v57 op_sel:[0,1,0] op_sel_hi:[0,1,0]
	v_mul_f32_e32 v190, 0xbfb8aa3b, v54
	v_mul_f32_e32 v191, 0xbfb8aa3b, v55
	v_mul_f32_e32 v192, 0xbfb8aa3b, v56
	v_mul_f32_e32 v193, 0xbfb8aa3b, v57
	v_exp_f32_e32 v190, v190
	v_exp_f32_e32 v191, v191
	v_exp_f32_e32 v192, v192
	v_exp_f32_e32 v193, v193
	v_add_f32_e32 v190, 1.0, v190
	v_add_f32_e32 v191, 1.0, v191
	v_add_f32_e32 v192, 1.0, v192
	v_add_f32_e32 v193, 1.0, v193
	v_rcp_f32_e32 v190, v190
	v_rcp_f32_e32 v191, v191
	v_rcp_f32_e32 v192, v192
	v_rcp_f32_e32 v193, v193
	s_nop 0
	v_pk_mul_f32 v[54:55], v[54:55], v[190:191]
	v_pk_mul_f32 v[56:57], v[56:57], v[192:193]
	v_pk_mul_f32 v[54:55], v[50:51], v[54:55]
	v_pk_mul_f32 v[56:57], v[52:53], v[56:57]
	v_cvt_pk_f16_f32 v54, v54, v55
	v_cvt_pk_f16_f32 v55, v56, v57
	global_store_dwordx2 v183, v[54:55], s[96:97] offset:32
	s_mov_b64 exec, s[4:5]
	v_add_u32_e32 v179, 0x6600, v201
	ds_read2_b64 v[154:157], v179 offset1:4
	ds_read2_b64 v[158:161], v179 offset0:68 offset1:72
	v_add_u32_e32 v180, 80, v200
	v_add_u32_e32 v181, s34, v180
	v_add_u32_e32 v182, -1, v180
	v_cmp_gt_u32_e32 vcc, 0xfe, v182
	v_cmp_gt_i32_e64 s[2:3], s6, v181
	v_cmp_gt_i32_e64 s[4:5], s68, v181
	v_mad_u32_u24 v183, v181, s52, v207
	s_and_b64 s[2:3], vcc, s[2:3]
	v_cndmask_b32_e64 v184, v216, v217, s[4:5]
	v_and_b32_e32 v185, v184, v181
	v_cmp_eq_u32_e32 vcc, 0, v185
	s_nop 1
	v_cndmask_b32_e64 v186, -1, 0, vcc
	v_cmp_eq_u32_e32 vcc, v185, v184
	s_nop 1
	v_cndmask_b32_e64 v188, -1, 0, vcc
	s_and_saveexec_b64 s[4:5], s[2:3]
	s_waitcnt lgkmcnt(2)
	v_pk_mul_f32 v[46:47], v[46:47], v[134:135]
	v_pk_mul_f32 v[48:49], v[48:49], v[136:137]
	v_and_b32_e32 v162, v186, v162
	v_and_b32_e32 v163, v186, v163
	v_and_b32_e32 v166, v188, v166
	v_and_b32_e32 v167, v188, v167
	v_fma_mix_f32 v46, v130, v162, v46 op_sel:[0,0,0] op_sel_hi:[0,1,0]
	v_fma_mix_f32 v47, v131, v162, v47 op_sel:[0,1,0] op_sel_hi:[0,1,0]
	v_fma_mix_f32 v48, v132, v163, v48 op_sel:[0,0,0] op_sel_hi:[0,1,0]
	v_fma_mix_f32 v49, v133, v163, v49 op_sel:[0,1,0] op_sel_hi:[0,1,0]
	v_fma_mix_f32 v46, v138, v166, v46 op_sel:[0,0,0] op_sel_hi:[0,1,0]
	v_fma_mix_f32 v47, v139, v166, v47 op_sel:[0,1,0] op_sel_hi:[0,1,0]
	v_fma_mix_f32 v48, v140, v167, v48 op_sel:[0,0,0] op_sel_hi:[0,1,0]
	v_fma_mix_f32 v49, v141, v167, v49 op_sel:[0,1,0] op_sel_hi:[0,1,0]
	v_mul_f32_e32 v190, 0xbfb8aa3b, v46
	v_mul_f32_e32 v191, 0xbfb8aa3b, v47
	v_mul_f32_e32 v192, 0xbfb8aa3b, v48
	v_mul_f32_e32 v193, 0xbfb8aa3b, v49
	v_exp_f32_e32 v190, v190
	v_exp_f32_e32 v191, v191
	v_exp_f32_e32 v192, v192
	v_exp_f32_e32 v193, v193
	v_add_f32_e32 v190, 1.0, v190
	v_add_f32_e32 v191, 1.0, v191
	v_add_f32_e32 v192, 1.0, v192
	v_add_f32_e32 v193, 1.0, v193
	v_rcp_f32_e32 v190, v190
	v_rcp_f32_e32 v191, v191
	v_rcp_f32_e32 v192, v192
	v_rcp_f32_e32 v193, v193
	s_nop 0
	v_pk_mul_f32 v[46:47], v[46:47], v[190:191]
	v_pk_mul_f32 v[48:49], v[48:49], v[192:193]
	v_pk_mul_f32 v[46:47], v[42:43], v[46:47]
	v_pk_mul_f32 v[48:49], v[44:45], v[48:49]
	v_cvt_pk_f16_f32 v46, v46, v47
	v_cvt_pk_f16_f32 v47, v48, v49
	global_store_dwordx2 v183, v[46:47], s[96:97]
	v_pk_mul_f32 v[38:39], v[38:39], v[146:147]
	v_pk_mul_f32 v[40:41], v[40:41], v[148:149]
	v_and_b32_e32 v164, v186, v164
	v_and_b32_e32 v165, v186, v165
	v_and_b32_e32 v168, v188, v168
	v_and_b32_e32 v169, v188, v169
	v_fma_mix_f32 v38, v142, v164, v38 op_sel:[0,0,0] op_sel_hi:[0,1,0]
	v_fma_mix_f32 v39, v143, v164, v39 op_sel:[0,1,0] op_sel_hi:[0,1,0]
	v_fma_mix_f32 v40, v144, v165, v40 op_sel:[0,0,0] op_sel_hi:[0,1,0]
	v_fma_mix_f32 v41, v145, v165, v41 op_sel:[0,1,0] op_sel_hi:[0,1,0]
	v_fma_mix_f32 v38, v150, v168, v38 op_sel:[0,0,0] op_sel_hi:[0,1,0]
	v_fma_mix_f32 v39, v151, v168, v39 op_sel:[0,1,0] op_sel_hi:[0,1,0]
	v_fma_mix_f32 v40, v152, v169, v40 op_sel:[0,0,0] op_sel_hi:[0,1,0]
	v_fma_mix_f32 v41, v153, v169, v41 op_sel:[0,1,0] op_sel_hi:[0,1,0]
	v_mul_f32_e32 v190, 0xbfb8aa3b, v38
	v_mul_f32_e32 v191, 0xbfb8aa3b, v39
	v_mul_f32_e32 v192, 0xbfb8aa3b, v40
	v_mul_f32_e32 v193, 0xbfb8aa3b, v41
	v_exp_f32_e32 v190, v190
	v_exp_f32_e32 v191, v191
	v_exp_f32_e32 v192, v192
	v_exp_f32_e32 v193, v193
	v_add_f32_e32 v190, 1.0, v190
	v_add_f32_e32 v191, 1.0, v191
	v_add_f32_e32 v192, 1.0, v192
	v_add_f32_e32 v193, 1.0, v193
	v_rcp_f32_e32 v190, v190
	v_rcp_f32_e32 v191, v191
	v_rcp_f32_e32 v192, v192
	v_rcp_f32_e32 v193, v193
	s_nop 0
	v_pk_mul_f32 v[38:39], v[38:39], v[190:191]
	v_pk_mul_f32 v[40:41], v[40:41], v[192:193]
	v_pk_mul_f32 v[38:39], v[34:35], v[38:39]
	v_pk_mul_f32 v[40:41], v[36:37], v[40:41]
	v_cvt_pk_f16_f32 v38, v38, v39
	v_cvt_pk_f16_f32 v39, v40, v41
	global_store_dwordx2 v183, v[38:39], s[96:97] offset:32
	s_mov_b64 exec, s[4:5]
	v_add_u32_e32 v179, 0x7700, v201
	ds_read2_b64 v[162:165], v179 offset1:4
	ds_read2_b64 v[166:169], v179 offset0:68 offset1:72
	v_add_u32_e32 v180, 96, v200
	v_add_u32_e32 v181, s34, v180
	v_add_u32_e32 v182, -1, v180
	v_cmp_gt_u32_e32 vcc, 0xfe, v182
	v_cmp_gt_i32_e64 s[2:3], s6, v181
	v_cmp_gt_i32_e64 s[4:5], s68, v181
	v_mad_u32_u24 v183, v181, s52, v207
	s_and_b64 s[2:3], vcc, s[2:3]
	v_cndmask_b32_e64 v184, v216, v217, s[4:5]
	v_and_b32_e32 v185, v184, v181
	v_cmp_eq_u32_e32 vcc, 0, v185
	s_nop 1
	v_cndmask_b32_e64 v186, -1, 0, vcc
	v_cmp_eq_u32_e32 vcc, v185, v184
	s_nop 1
	v_cndmask_b32_e64 v188, -1, 0, vcc
	s_and_saveexec_b64 s[4:5], s[2:3]
	s_waitcnt lgkmcnt(2)
	v_pk_mul_f32 v[30:31], v[30:31], v[134:135]
	v_pk_mul_f32 v[32:33], v[32:33], v[136:137]
	v_and_b32_e32 v154, v186, v154
	v_and_b32_e32 v155, v186, v155
	v_and_b32_e32 v158, v188, v158
	v_and_b32_e32 v159, v188, v159
	v_fma_mix_f32 v30, v130, v154, v30 op_sel:[0,0,0] op_sel_hi:[0,1,0]
	v_fma_mix_f32 v31, v131, v154, v31 op_sel:[0,1,0] op_sel_hi:[0,1,0]
	v_fma_mix_f32 v32, v132, v155, v32 op_sel:[0,0,0] op_sel_hi:[0,1,0]
	v_fma_mix_f32 v33, v133, v155, v33 op_sel:[0,1,0] op_sel_hi:[0,1,0]
	v_fma_mix_f32 v30, v138, v158, v30 op_sel:[0,0,0] op_sel_hi:[0,1,0]
	v_fma_mix_f32 v31, v139, v158, v31 op_sel:[0,1,0] op_sel_hi:[0,1,0]
	v_fma_mix_f32 v32, v140, v159, v32 op_sel:[0,0,0] op_sel_hi:[0,1,0]
	v_fma_mix_f32 v33, v141, v159, v33 op_sel:[0,1,0] op_sel_hi:[0,1,0]
	v_mul_f32_e32 v190, 0xbfb8aa3b, v30
	v_mul_f32_e32 v191, 0xbfb8aa3b, v31
	v_mul_f32_e32 v192, 0xbfb8aa3b, v32
	v_mul_f32_e32 v193, 0xbfb8aa3b, v33
	v_exp_f32_e32 v190, v190
	v_exp_f32_e32 v191, v191
	v_exp_f32_e32 v192, v192
	v_exp_f32_e32 v193, v193
	v_add_f32_e32 v190, 1.0, v190
	v_add_f32_e32 v191, 1.0, v191
	v_add_f32_e32 v192, 1.0, v192
	v_add_f32_e32 v193, 1.0, v193
	v_rcp_f32_e32 v190, v190
	v_rcp_f32_e32 v191, v191
	v_rcp_f32_e32 v192, v192
	v_rcp_f32_e32 v193, v193
	s_nop 0
	v_pk_mul_f32 v[30:31], v[30:31], v[190:191]
	v_pk_mul_f32 v[32:33], v[32:33], v[192:193]
	v_pk_mul_f32 v[30:31], v[26:27], v[30:31]
	v_pk_mul_f32 v[32:33], v[28:29], v[32:33]
	v_cvt_pk_f16_f32 v30, v30, v31
	v_cvt_pk_f16_f32 v31, v32, v33
	global_store_dwordx2 v183, v[30:31], s[96:97]
	v_pk_mul_f32 v[22:23], v[22:23], v[146:147]
	v_pk_mul_f32 v[24:25], v[24:25], v[148:149]
	v_and_b32_e32 v156, v186, v156
	v_and_b32_e32 v157, v186, v157
	v_and_b32_e32 v160, v188, v160
	v_and_b32_e32 v161, v188, v161
	v_fma_mix_f32 v22, v142, v156, v22 op_sel:[0,0,0] op_sel_hi:[0,1,0]
	v_fma_mix_f32 v23, v143, v156, v23 op_sel:[0,1,0] op_sel_hi:[0,1,0]
	v_fma_mix_f32 v24, v144, v157, v24 op_sel:[0,0,0] op_sel_hi:[0,1,0]
	v_fma_mix_f32 v25, v145, v157, v25 op_sel:[0,1,0] op_sel_hi:[0,1,0]
	v_fma_mix_f32 v22, v150, v160, v22 op_sel:[0,0,0] op_sel_hi:[0,1,0]
	v_fma_mix_f32 v23, v151, v160, v23 op_sel:[0,1,0] op_sel_hi:[0,1,0]
	v_fma_mix_f32 v24, v152, v161, v24 op_sel:[0,0,0] op_sel_hi:[0,1,0]
	v_fma_mix_f32 v25, v153, v161, v25 op_sel:[0,1,0] op_sel_hi:[0,1,0]
	v_mul_f32_e32 v190, 0xbfb8aa3b, v22
	v_mul_f32_e32 v191, 0xbfb8aa3b, v23
	v_mul_f32_e32 v192, 0xbfb8aa3b, v24
	v_mul_f32_e32 v193, 0xbfb8aa3b, v25
	v_exp_f32_e32 v190, v190
	v_exp_f32_e32 v191, v191
	v_exp_f32_e32 v192, v192
	v_exp_f32_e32 v193, v193
	v_add_f32_e32 v190, 1.0, v190
	v_add_f32_e32 v191, 1.0, v191
	v_add_f32_e32 v192, 1.0, v192
	v_add_f32_e32 v193, 1.0, v193
	v_rcp_f32_e32 v190, v190
	v_rcp_f32_e32 v191, v191
	v_rcp_f32_e32 v192, v192
	v_rcp_f32_e32 v193, v193
	s_nop 0
	v_pk_mul_f32 v[22:23], v[22:23], v[190:191]
	v_pk_mul_f32 v[24:25], v[24:25], v[192:193]
	v_pk_mul_f32 v[22:23], v[18:19], v[22:23]
	v_pk_mul_f32 v[24:25], v[20:21], v[24:25]
	v_cvt_pk_f16_f32 v22, v22, v23
	v_cvt_pk_f16_f32 v23, v24, v25
	global_store_dwordx2 v183, v[22:23], s[96:97] offset:32
	s_mov_b64 exec, s[4:5]
	v_add_u32_e32 v180, 112, v200
	v_add_u32_e32 v181, s34, v180
	v_add_u32_e32 v182, -1, v180
	v_cmp_gt_u32_e32 vcc, 0xfe, v182
	v_cmp_gt_i32_e64 s[2:3], s6, v181
	v_cmp_gt_i32_e64 s[4:5], s68, v181
	v_mad_u32_u24 v183, v181, s52, v207
	s_and_b64 s[2:3], vcc, s[2:3]
	v_cndmask_b32_e64 v184, v216, v217, s[4:5]
	v_and_b32_e32 v185, v184, v181
	v_cmp_eq_u32_e32 vcc, 0, v185
	s_nop 1
	v_cndmask_b32_e64 v186, -1, 0, vcc
	v_cmp_eq_u32_e32 vcc, v185, v184
	s_nop 1
	v_cndmask_b32_e64 v188, -1, 0, vcc
	s_and_saveexec_b64 s[4:5], s[2:3]
	s_waitcnt lgkmcnt(0)
	v_pk_mul_f32 v[14:15], v[14:15], v[134:135]
	v_pk_mul_f32 v[16:17], v[16:17], v[136:137]
	v_and_b32_e32 v162, v186, v162
	v_and_b32_e32 v163, v186, v163
	v_and_b32_e32 v166, v188, v166
	v_and_b32_e32 v167, v188, v167
	v_fma_mix_f32 v14, v130, v162, v14 op_sel:[0,0,0] op_sel_hi:[0,1,0]
	v_fma_mix_f32 v15, v131, v162, v15 op_sel:[0,1,0] op_sel_hi:[0,1,0]
	v_fma_mix_f32 v16, v132, v163, v16 op_sel:[0,0,0] op_sel_hi:[0,1,0]
	v_fma_mix_f32 v17, v133, v163, v17 op_sel:[0,1,0] op_sel_hi:[0,1,0]
	v_fma_mix_f32 v14, v138, v166, v14 op_sel:[0,0,0] op_sel_hi:[0,1,0]
	v_fma_mix_f32 v15, v139, v166, v15 op_sel:[0,1,0] op_sel_hi:[0,1,0]
	v_fma_mix_f32 v16, v140, v167, v16 op_sel:[0,0,0] op_sel_hi:[0,1,0]
	v_fma_mix_f32 v17, v141, v167, v17 op_sel:[0,1,0] op_sel_hi:[0,1,0]
	v_mul_f32_e32 v190, 0xbfb8aa3b, v14
	v_mul_f32_e32 v191, 0xbfb8aa3b, v15
	v_mul_f32_e32 v192, 0xbfb8aa3b, v16
	v_mul_f32_e32 v193, 0xbfb8aa3b, v17
	v_exp_f32_e32 v190, v190
	v_exp_f32_e32 v191, v191
	v_exp_f32_e32 v192, v192
	v_exp_f32_e32 v193, v193
	v_add_f32_e32 v190, 1.0, v190
	v_add_f32_e32 v191, 1.0, v191
	v_add_f32_e32 v192, 1.0, v192
	v_add_f32_e32 v193, 1.0, v193
	v_rcp_f32_e32 v190, v190
	v_rcp_f32_e32 v191, v191
	v_rcp_f32_e32 v192, v192
	v_rcp_f32_e32 v193, v193
	s_nop 0
	v_pk_mul_f32 v[14:15], v[14:15], v[190:191]
	v_pk_mul_f32 v[16:17], v[16:17], v[192:193]
	v_pk_mul_f32 v[14:15], v[10:11], v[14:15]
	v_pk_mul_f32 v[16:17], v[12:13], v[16:17]
	v_cvt_pk_f16_f32 v14, v14, v15
	v_cvt_pk_f16_f32 v15, v16, v17
	global_store_dwordx2 v183, v[14:15], s[96:97]
	v_pk_mul_f32 v[6:7], v[6:7], v[146:147]
	v_pk_mul_f32 v[8:9], v[8:9], v[148:149]
	v_and_b32_e32 v164, v186, v164
	v_and_b32_e32 v165, v186, v165
	v_and_b32_e32 v168, v188, v168
	v_and_b32_e32 v169, v188, v169
	v_fma_mix_f32 v6, v142, v164, v6 op_sel:[0,0,0] op_sel_hi:[0,1,0]
	v_fma_mix_f32 v7, v143, v164, v7 op_sel:[0,1,0] op_sel_hi:[0,1,0]
	v_fma_mix_f32 v8, v144, v165, v8 op_sel:[0,0,0] op_sel_hi:[0,1,0]
	v_fma_mix_f32 v9, v145, v165, v9 op_sel:[0,1,0] op_sel_hi:[0,1,0]
	v_fma_mix_f32 v6, v150, v168, v6 op_sel:[0,0,0] op_sel_hi:[0,1,0]
	v_fma_mix_f32 v7, v151, v168, v7 op_sel:[0,1,0] op_sel_hi:[0,1,0]
	v_fma_mix_f32 v8, v152, v169, v8 op_sel:[0,0,0] op_sel_hi:[0,1,0]
	v_fma_mix_f32 v9, v153, v169, v9 op_sel:[0,1,0] op_sel_hi:[0,1,0]
	v_mul_f32_e32 v190, 0xbfb8aa3b, v6
	v_mul_f32_e32 v191, 0xbfb8aa3b, v7
	v_mul_f32_e32 v192, 0xbfb8aa3b, v8
	v_mul_f32_e32 v193, 0xbfb8aa3b, v9
	v_exp_f32_e32 v190, v190
	v_exp_f32_e32 v191, v191
	v_exp_f32_e32 v192, v192
	v_exp_f32_e32 v193, v193
	v_add_f32_e32 v190, 1.0, v190
	v_add_f32_e32 v191, 1.0, v191
	v_add_f32_e32 v192, 1.0, v192
	v_add_f32_e32 v193, 1.0, v193
	v_rcp_f32_e32 v190, v190
	v_rcp_f32_e32 v191, v191
	v_rcp_f32_e32 v192, v192
	v_rcp_f32_e32 v193, v193
	s_nop 0
	v_pk_mul_f32 v[6:7], v[6:7], v[190:191]
	v_pk_mul_f32 v[8:9], v[8:9], v[192:193]
	v_pk_mul_f32 v[6:7], v[2:3], v[6:7]
	v_pk_mul_f32 v[8:9], v[4:5], v[8:9]
	v_cvt_pk_f16_f32 v6, v6, v7
	v_cvt_pk_f16_f32 v7, v8, v9
	global_store_dwordx2 v183, v[6:7], s[96:97] offset:32
	s_mov_b64 exec, s[4:5]
	s_cmp_lg_u32 s35, 0
	s_cbranch_scc1 .Lp4_cont
	s_cmp_lg_u32 s6, 0x8000
	s_cbranch_scc1 .Lp4t_none
	v_readlane_b32 s2, v255, 22
	s_nop 0
	s_cmp_ge_u32 s2, 0x6e
	s_cbranch_scc1 .Lp4t_none
	s_mul_i32 s3, s2, 0xba3
	s_lshr_b32 s3, s3, 16
	s_mul_i32 s4, s3, 22
	s_sub_i32 s18, s2, s4
	s_mul_i32 s28, s3, 62
	s_add_i32 s28, s28, 0x7eff
	s_waitcnt vmcnt(0)
	v_lshrrev_b32_e32 v202, 3, v222
	v_lshrrev_b32_e32 v203, 4, v222
	v_xor_b32_e32 v203, v203, v222
	v_and_b32_e32 v203, 7, v203
	v_lshlrev_b32_e32 v210, 4, v203
	v_mov_b32_e32 v200, s46
	v_mov_b32_e32 v201, s47
	v_add_u32_e32 v204, s28, v202
	v_mov_b32_e32 v205, 0
	v_cmp_gt_u32_e32 vcc, s6, v204
	v_lshlrev_b64 v[196:197], 11, v[204:205]
	v_lshl_add_u64 v[196:197], s[64:65], 0, v[196:197]
	v_cndmask_b32_e32 v196, v200, v196, vcc
	v_cndmask_b32_e32 v197, v201, v197, vcc
	v_lshl_add_u64 v[218:219], v[196:197], 0, v[210:211]
	v_cmp_gt_u32_e32 vcc, s6, v204
	v_lshlrev_b64 v[196:197], 11, v[204:205]
	v_lshl_add_u64 v[196:197], s[64:65], 0, v[196:197]
	v_cndmask_b32_e32 v196, v200, v196, vcc
	v_cndmask_b32_e32 v197, v201, v197, vcc
	v_lshl_add_u64 v[220:221], v[196:197], 0, v[210:211]
	v_cmp_gt_u32_e32 vcc, s6, v204
	v_lshlrev_b64 v[196:197], 11, v[204:205]
	v_lshl_add_u64 v[196:197], s[64:65], 0, v[196:197]
	v_cndmask_b32_e32 v196, v200, v196, vcc
	v_cndmask_b32_e32 v197, v201, v197, vcc
	v_lshl_add_u64 v[224:225], v[196:197], 0, v[210:211]
	v_cmp_gt_u32_e32 vcc, s6, v204
	v_lshlrev_b64 v[196:197], 11, v[204:205]
	v_lshl_add_u64 v[196:197], s[64:65], 0, v[196:197]
	v_cndmask_b32_e32 v196, v200, v196, vcc
	v_cndmask_b32_e32 v197, v201, v197, vcc
	v_lshl_add_u64 v[226:227], v[196:197], 0, v[210:211]
	s_lshl_b32 s2, s18, 19
	s_add_u32 s2, s55, s2
	s_addc_u32 s3, s48, 0
	v_lshlrev_b32_e32 v196, 11, v202
	v_add_u32_e32 v196, v196, v210
	v_mov_b32_e32 v197, 0
	v_lshl_add_u64 v[228:229], v[196:197], 0, s[2:3]
	v_and_b32_e32 v196, 15, v222
	v_bfe_u32 v197, v222, 4, 2
	v_bfe_u32 v198, v196, 1, 3
	v_xor_b32_e32 v197, v197, v198
	v_lshlrev_b32_e32 v197, 4, v197
	v_lshrrev_b32_e32 v198, 8, v222
	v_lshl_or_b32 v198, v198, 5, v196
	v_lshl_or_b32 v188, v198, 7, v197
	v_xor_b32_e32 v189, 64, v188
	v_bfe_u32 v198, v222, 6, 2
	v_lshl_or_b32 v198, v198, 6, v196
	v_lshl_or_b32 v190, v198, 7, v197
	v_xor_b32_e32 v191, 64, v190
	v_add_u32_e32 v192, 0x10000, v188
	v_add_u32_e32 v193, 0x10000, v189
	v_add_u32_e32 v194, 0x10000, v190
	v_add_u32_e32 v195, 0x10000, v191
	v_readfirstlane_b32 s19, v222
	s_nop 3
	s_lshr_b32 s29, s19, 8
	s_lshr_b32 s19, s19, 6
	s_lshl_b32 s19, s19, 10
	s_mov_b32 s20, 0
	s_mov_b32 s21, 0
	s_mov_b32 s23, 0
	s_barrier
	s_mov_b32 m0, s19
	v_lshl_add_u64 v[196:197], v[218:219], 0, s[20:21]
	global_load_lds_dwordx4 v[196:197], off
	s_add_i32 m0, s19, 0x2000
	v_lshl_add_u64 v[198:199], v[220:221], 0, s[20:21]
	global_load_lds_dwordx4 v[198:199], off
	s_add_i32 m0, s19, 0x4000
	v_lshl_add_u64 v[196:197], v[224:225], 0, s[20:21]
	global_load_lds_dwordx4 v[196:197], off
	s_add_i32 m0, s19, 0x6000
	v_lshl_add_u64 v[198:199], v[226:227], 0, s[20:21]
	global_load_lds_dwordx4 v[198:199], off
	s_add_i32 m0, s19, 0x8000
	v_lshl_add_u64 v[196:197], v[228:229], 0, s[20:21]
	global_load_lds_dwordx4 v[196:197], off
	s_add_u32 s22, s20, 0x20000
	s_add_i32 m0, s19, 0xa000
	v_lshl_add_u64 v[198:199], v[228:229], 0, s[22:23]
	global_load_lds_dwordx4 v[198:199], off
	s_add_u32 s22, s20, 0x40000
	s_add_i32 m0, s19, 0xc000
	v_lshl_add_u64 v[196:197], v[228:229], 0, s[22:23]
	global_load_lds_dwordx4 v[196:197], off
	s_add_u32 s22, s20, 0x60000
	s_add_i32 m0, s19, 0xe000
	v_lshl_add_u64 v[198:199], v[228:229], 0, s[22:23]
	global_load_lds_dwordx4 v[198:199], off
	s_add_u32 s22, s20, 0x80
	s_add_i32 m0, s19, 0x10000
	v_lshl_add_u64 v[196:197], v[218:219], 0, s[22:23]
	global_load_lds_dwordx4 v[196:197], off
	s_add_u32 s22, s20, 0x80
	s_add_i32 m0, s19, 0x18000
	v_lshl_add_u64 v[198:199], v[228:229], 0, s[22:23]
	global_load_lds_dwordx4 v[198:199], off
	s_waitcnt vmcnt(2)
	s_barrier
	s_cmp_eq_u32 s29, 0
	s_cbranch_scc1 .Lp4t_skew0
	s_barrier
.Lp4t_skew0:
	ds_read_b128 v[130:133], v188 offset:0
	ds_read_b128 v[134:137], v188 offset:2048
	ds_read_b128 v[162:165], v190 offset:32768
	ds_read_b128 v[166:169], v190 offset:34816
	ds_read_b128 v[170:173], v190 offset:36864
	ds_read_b128 v[174:177], v190 offset:38912
	s_add_u32 s22, s20, 0x80
	s_add_i32 m0, s19, 0x14000
	v_lshl_add_u64 v[196:197], v[224:225], 0, s[22:23]
	global_load_lds_dwordx4 v[196:197], off
	s_add_u32 s22, s20, 0x20080
	s_add_i32 m0, s19, 0x1a000
	v_lshl_add_u64 v[198:199], v[228:229], 0, s[22:23]
	global_load_lds_dwordx4 v[198:199], off
	s_waitcnt lgkmcnt(0)
	s_barrier
	v_mfma_f32_16x16x32_f16 v[126:129], v[162:165], v[130:133], 0
	v_mfma_f32_16x16x32_f16 v[122:125], v[166:169], v[130:133], 0
	v_mfma_f32_16x16x32_f16 v[118:121], v[170:173], v[130:133], 0
	v_mfma_f32_16x16x32_f16 v[114:117], v[174:177], v[130:133], 0
	v_mfma_f32_16x16x32_f16 v[110:113], v[162:165], v[134:137], 0
	v_mfma_f32_16x16x32_f16 v[106:109], v[166:169], v[134:137], 0
	v_mfma_f32_16x16x32_f16 v[102:105], v[170:173], v[134:137], 0
	v_mfma_f32_16x16x32_f16 v[98:101], v[174:177], v[134:137], 0
	s_barrier
	s_add_u32 s22, s20, 0x40080
	s_add_i32 m0, s19, 0x1c000
	v_lshl_add_u64 v[196:197], v[228:229], 0, s[22:23]
	global_load_lds_dwordx4 v[196:197], off
	s_add_u32 s22, s20, 0x60080
	s_add_i32 m0, s19, 0x1e000
	v_lshl_add_u64 v[198:199], v[228:229], 0, s[22:23]
	global_load_lds_dwordx4 v[198:199], off
	s_waitcnt lgkmcnt(0)
	s_barrier
	s_barrier
	ds_read_b128 v[130:133], v189 offset:0
	ds_read_b128 v[134:137], v189 offset:2048
	ds_read_b128 v[162:165], v191 offset:32768
	ds_read_b128 v[166:169], v191 offset:34816
	ds_read_b128 v[170:173], v191 offset:36864
	ds_read_b128 v[174:177], v191 offset:38912
	s_add_u32 s22, s20, 0x80
	s_add_i32 m0, s19, 0x12000
	v_lshl_add_u64 v[196:197], v[220:221], 0, s[22:23]
	global_load_lds_dwordx4 v[196:197], off
	s_add_u32 s22, s20, 0x80
	s_add_i32 m0, s19, 0x16000
	v_lshl_add_u64 v[198:199], v[226:227], 0, s[22:23]
	global_load_lds_dwordx4 v[198:199], off
	s_waitcnt lgkmcnt(0)
	s_barrier
	v_mfma_f32_16x16x32_f16 v[126:129], v[162:165], v[130:133], v[126:129]
	v_mfma_f32_16x16x32_f16 v[122:125], v[166:169], v[130:133], v[122:125]
	v_mfma_f32_16x16x32_f16 v[118:121], v[170:173], v[130:133], v[118:121]
	v_mfma_f32_16x16x32_f16 v[114:117], v[174:177], v[130:133], v[114:117]
	v_mfma_f32_16x16x32_f16 v[110:113], v[162:165], v[134:137], v[110:113]
	v_mfma_f32_16x16x32_f16 v[106:109], v[166:169], v[134:137], v[106:109]
	v_mfma_f32_16x16x32_f16 v[102:105], v[170:173], v[134:137], v[102:105]
	v_mfma_f32_16x16x32_f16 v[98:101], v[174:177], v[134:137], v[98:101]
	s_barrier
	s_add_u32 s22, s20, 0x100
	s_mov_b32 m0, s19
	v_lshl_add_u64 v[196:197], v[218:219], 0, s[22:23]
	global_load_lds_dwordx4 v[196:197], off
	s_add_u32 s22, s20, 0x100
	s_add_i32 m0, s19, 0x8000
	v_lshl_add_u64 v[198:199], v[228:229], 0, s[22:23]
	global_load_lds_dwordx4 v[198:199], off
	s_waitcnt vmcnt(4) lgkmcnt(0)
	s_barrier
	s_barrier
	s_add_u32 s20, s20, 0x80
	ds_read_b128 v[130:133], v192 offset:0
	ds_read_b128 v[134:137], v192 offset:2048
	ds_read_b128 v[162:165], v194 offset:32768
	ds_read_b128 v[166:169], v194 offset:34816
	ds_read_b128 v[170:173], v194 offset:36864
	ds_read_b128 v[174:177], v194 offset:38912
	s_add_u32 s22, s20, 0x80
	s_add_i32 m0, s19, 0x4000
	v_lshl_add_u64 v[196:197], v[224:225], 0, s[22:23]
	global_load_lds_dwordx4 v[196:197], off
	s_add_u32 s22, s20, 0x20080
	s_add_i32 m0, s19, 0xa000
	v_lshl_add_u64 v[198:199], v[228:229], 0, s[22:23]
	global_load_lds_dwordx4 v[198:199], off
	s_waitcnt vmcnt(4) lgkmcnt(0)
	s_barrier
	v_mfma_f32_16x16x32_f16 v[126:129], v[162:165], v[130:133], v[126:129]
	v_mfma_f32_16x16x32_f16 v[122:125], v[166:169], v[130:133], v[122:125]
	v_mfma_f32_16x16x32_f16 v[118:121], v[170:173], v[130:133], v[118:121]
	v_mfma_f32_16x16x32_f16 v[114:117], v[174:177], v[130:133], v[114:117]
	v_mfma_f32_16x16x32_f16 v[110:113], v[162:165], v[134:137], v[110:113]
	v_mfma_f32_16x16x32_f16 v[106:109], v[166:169], v[134:137], v[106:109]
	v_mfma_f32_16x16x32_f16 v[102:105], v[170:173], v[134:137], v[102:105]
	v_mfma_f32_16x16x32_f16 v[98:101], v[174:177], v[134:137], v[98:101]
	s_barrier
	s_add_u32 s22, s20, 0x40080
	s_add_i32 m0, s19, 0xc000
	v_lshl_add_u64 v[196:197], v[228:229], 0, s[22:23]
	global_load_lds_dwordx4 v[196:197], off
	s_add_u32 s22, s20, 0x60080
	s_add_i32 m0, s19, 0xe000
	v_lshl_add_u64 v[198:199], v[228:229], 0, s[22:23]
	global_load_lds_dwordx4 v[198:199], off
	s_waitcnt lgkmcnt(0)
	s_barrier
	s_barrier
	ds_read_b128 v[130:133], v193 offset:0
	ds_read_b128 v[134:137], v193 offset:2048
	ds_read_b128 v[162:165], v195 offset:32768
	ds_read_b128 v[166:169], v195 offset:34816
	ds_read_b128 v[170:173], v195 offset:36864
	ds_read_b128 v[174:177], v195 offset:38912
	s_add_u32 s22, s20, 0x80
	s_add_i32 m0, s19, 0x2000
	v_lshl_add_u64 v[196:197], v[220:221], 0, s[22:23]
	global_load_lds_dwordx4 v[196:197], off
	s_add_u32 s22, s20, 0x80
	s_add_i32 m0, s19, 0x6000
	v_lshl_add_u64 v[198:199], v[226:227], 0, s[22:23]
	global_load_lds_dwordx4 v[198:199], off
	s_waitcnt lgkmcnt(0)
	s_barrier
	v_mfma_f32_16x16x32_f16 v[126:129], v[162:165], v[130:133], v[126:129]
	v_mfma_f32_16x16x32_f16 v[122:125], v[166:169], v[130:133], v[122:125]
	v_mfma_f32_16x16x32_f16 v[118:121], v[170:173], v[130:133], v[118:121]
	v_mfma_f32_16x16x32_f16 v[114:117], v[174:177], v[130:133], v[114:117]
	v_mfma_f32_16x16x32_f16 v[110:113], v[162:165], v[134:137], v[110:113]
	v_mfma_f32_16x16x32_f16 v[106:109], v[166:169], v[134:137], v[106:109]
	v_mfma_f32_16x16x32_f16 v[102:105], v[170:173], v[134:137], v[102:105]
	v_mfma_f32_16x16x32_f16 v[98:101], v[174:177], v[134:137], v[98:101]
	s_barrier
	s_add_u32 s22, s20, 0x100
	s_add_i32 m0, s19, 0x10000
	v_lshl_add_u64 v[196:197], v[218:219], 0, s[22:23]
	global_load_lds_dwordx4 v[196:197], off
	s_add_u32 s22, s20, 0x100
	s_add_i32 m0, s19, 0x18000
	v_lshl_add_u64 v[198:199], v[228:229], 0, s[22:23]
	global_load_lds_dwordx4 v[198:199], off
	s_waitcnt vmcnt(4) lgkmcnt(0)
	s_barrier
	s_barrier
	s_add_u32 s20, s20, 0x80
	s_movk_i32 s33, 6
.Lp4t_loop:
	ds_read_b128 v[130:133], v188 offset:0
	ds_read_b128 v[134:137], v188 offset:2048
	ds_read_b128 v[162:165], v190 offset:32768
	ds_read_b128 v[166:169], v190 offset:34816
	ds_read_b128 v[170:173], v190 offset:36864
	ds_read_b128 v[174:177], v190 offset:38912
	s_add_u32 s22, s20, 0x80
	s_add_i32 m0, s19, 0x14000
	v_lshl_add_u64 v[196:197], v[224:225], 0, s[22:23]
	global_load_lds_dwordx4 v[196:197], off
	s_add_u32 s22, s20, 0x20080
	s_add_i32 m0, s19, 0x1a000
	v_lshl_add_u64 v[198:199], v[228:229], 0, s[22:23]
	global_load_lds_dwordx4 v[198:199], off
	s_waitcnt vmcnt(4) lgkmcnt(0)
	s_barrier
	v_mfma_f32_16x16x32_f16 v[126:129], v[162:165], v[130:133], v[126:129]
	v_mfma_f32_16x16x32_f16 v[122:125], v[166:169], v[130:133], v[122:125]
	v_mfma_f32_16x16x32_f16 v[118:121], v[170:173], v[130:133], v[118:121]
	v_mfma_f32_16x16x32_f16 v[114:117], v[174:177], v[130:133], v[114:117]
	v_mfma_f32_16x16x32_f16 v[110:113], v[162:165], v[134:137], v[110:113]
	v_mfma_f32_16x16x32_f16 v[106:109], v[166:169], v[134:137], v[106:109]
	v_mfma_f32_16x16x32_f16 v[102:105], v[170:173], v[134:137], v[102:105]
	v_mfma_f32_16x16x32_f16 v[98:101], v[174:177], v[134:137], v[98:101]
	s_barrier
	s_add_u32 s22, s20, 0x40080
	s_add_i32 m0, s19, 0x1c000
	v_lshl_add_u64 v[196:197], v[228:229], 0, s[22:23]
	global_load_lds_dwordx4 v[196:197], off
	s_add_u32 s22, s20, 0x60080
	s_add_i32 m0, s19, 0x1e000
	v_lshl_add_u64 v[198:199], v[228:229], 0, s[22:23]
	global_load_lds_dwordx4 v[198:199], off
	s_waitcnt lgkmcnt(0)
	s_barrier
	s_barrier
	ds_read_b128 v[130:133], v189 offset:0
	ds_read_b128 v[134:137], v189 offset:2048
	ds_read_b128 v[162:165], v191 offset:32768
	ds_read_b128 v[166:169], v191 offset:34816
	ds_read_b128 v[170:173], v191 offset:36864
	ds_read_b128 v[174:177], v191 offset:38912
	s_add_u32 s22, s20, 0x80
	s_add_i32 m0, s19, 0x12000
	v_lshl_add_u64 v[196:197], v[220:221], 0, s[22:23]
	global_load_lds_dwordx4 v[196:197], off
	s_add_u32 s22, s20, 0x80
	s_add_i32 m0, s19, 0x16000
	v_lshl_add_u64 v[198:199], v[226:227], 0, s[22:23]
	global_load_lds_dwordx4 v[198:199], off
	s_waitcnt lgkmcnt(0)
	s_barrier
	v_mfma_f32_16x16x32_f16 v[126:129], v[162:165], v[130:133], v[126:129]
	v_mfma_f32_16x16x32_f16 v[122:125], v[166:169], v[130:133], v[122:125]
	v_mfma_f32_16x16x32_f16 v[118:121], v[170:173], v[130:133], v[118:121]
	v_mfma_f32_16x16x32_f16 v[114:117], v[174:177], v[130:133], v[114:117]
	v_mfma_f32_16x16x32_f16 v[110:113], v[162:165], v[134:137], v[110:113]
	v_mfma_f32_16x16x32_f16 v[106:109], v[166:169], v[134:137], v[106:109]
	v_mfma_f32_16x16x32_f16 v[102:105], v[170:173], v[134:137], v[102:105]
	v_mfma_f32_16x16x32_f16 v[98:101], v[174:177], v[134:137], v[98:101]
	s_barrier
	s_add_u32 s22, s20, 0x100
	s_mov_b32 m0, s19
	v_lshl_add_u64 v[196:197], v[218:219], 0, s[22:23]
	global_load_lds_dwordx4 v[196:197], off
	s_add_u32 s22, s20, 0x100
	s_add_i32 m0, s19, 0x8000
	v_lshl_add_u64 v[198:199], v[228:229], 0, s[22:23]
	global_load_lds_dwordx4 v[198:199], off
	s_waitcnt vmcnt(4) lgkmcnt(0)
	s_barrier
	s_barrier
	s_add_u32 s20, s20, 0x80
	ds_read_b128 v[130:133], v192 offset:0
	ds_read_b128 v[134:137], v192 offset:2048
	ds_read_b128 v[162:165], v194 offset:32768
	ds_read_b128 v[166:169], v194 offset:34816
	ds_read_b128 v[170:173], v194 offset:36864
	ds_read_b128 v[174:177], v194 offset:38912
	s_add_u32 s22, s20, 0x80
	s_add_i32 m0, s19, 0x4000
	v_lshl_add_u64 v[196:197], v[224:225], 0, s[22:23]
	global_load_lds_dwordx4 v[196:197], off
	s_add_u32 s22, s20, 0x20080
	s_add_i32 m0, s19, 0xa000
	v_lshl_add_u64 v[198:199], v[228:229], 0, s[22:23]
	global_load_lds_dwordx4 v[198:199], off
	s_waitcnt vmcnt(4) lgkmcnt(0)
	s_barrier
	v_mfma_f32_16x16x32_f16 v[126:129], v[162:165], v[130:133], v[126:129]
	v_mfma_f32_16x16x32_f16 v[122:125], v[166:169], v[130:133], v[122:125]
	v_mfma_f32_16x16x32_f16 v[118:121], v[170:173], v[130:133], v[118:121]
	v_mfma_f32_16x16x32_f16 v[114:117], v[174:177], v[130:133], v[114:117]
	v_mfma_f32_16x16x32_f16 v[110:113], v[162:165], v[134:137], v[110:113]
	v_mfma_f32_16x16x32_f16 v[106:109], v[166:169], v[134:137], v[106:109]
	v_mfma_f32_16x16x32_f16 v[102:105], v[170:173], v[134:137], v[102:105]
	v_mfma_f32_16x16x32_f16 v[98:101], v[174:177], v[134:137], v[98:101]
	s_barrier
	s_add_u32 s22, s20, 0x40080
	s_add_i32 m0, s19, 0xc000
	v_lshl_add_u64 v[196:197], v[228:229], 0, s[22:23]
	global_load_lds_dwordx4 v[196:197], off
	s_add_u32 s22, s20, 0x60080
	s_add_i32 m0, s19, 0xe000
	v_lshl_add_u64 v[198:199], v[228:229], 0, s[22:23]
	global_load_lds_dwordx4 v[198:199], off
	s_waitcnt lgkmcnt(0)
	s_barrier
	s_barrier
	ds_read_b128 v[130:133], v193 offset:0
	ds_read_b128 v[134:137], v193 offset:2048
	ds_read_b128 v[162:165], v195 offset:32768
	ds_read_b128 v[166:169], v195 offset:34816
	ds_read_b128 v[170:173], v195 offset:36864
	ds_read_b128 v[174:177], v195 offset:38912
	s_add_u32 s22, s20, 0x80
	s_add_i32 m0, s19, 0x2000
	v_lshl_add_u64 v[196:197], v[220:221], 0, s[22:23]
	global_load_lds_dwordx4 v[196:197], off
	s_add_u32 s22, s20, 0x80
	s_add_i32 m0, s19, 0x6000
	v_lshl_add_u64 v[198:199], v[226:227], 0, s[22:23]
	global_load_lds_dwordx4 v[198:199], off
	s_waitcnt lgkmcnt(0)
	s_barrier
	v_mfma_f32_16x16x32_f16 v[126:129], v[162:165], v[130:133], v[126:129]
	v_mfma_f32_16x16x32_f16 v[122:125], v[166:169], v[130:133], v[122:125]
	v_mfma_f32_16x16x32_f16 v[118:121], v[170:173], v[130:133], v[118:121]
	v_mfma_f32_16x16x32_f16 v[114:117], v[174:177], v[130:133], v[114:117]
	v_mfma_f32_16x16x32_f16 v[110:113], v[162:165], v[134:137], v[110:113]
	v_mfma_f32_16x16x32_f16 v[106:109], v[166:169], v[134:137], v[106:109]
	v_mfma_f32_16x16x32_f16 v[102:105], v[170:173], v[134:137], v[102:105]
	v_mfma_f32_16x16x32_f16 v[98:101], v[174:177], v[134:137], v[98:101]
	s_barrier
	s_add_u32 s22, s20, 0x100
	s_add_i32 m0, s19, 0x10000
	v_lshl_add_u64 v[196:197], v[218:219], 0, s[22:23]
	global_load_lds_dwordx4 v[196:197], off
	s_add_u32 s22, s20, 0x100
	s_add_i32 m0, s19, 0x18000
	v_lshl_add_u64 v[198:199], v[228:229], 0, s[22:23]
	global_load_lds_dwordx4 v[198:199], off
	s_waitcnt vmcnt(4) lgkmcnt(0)
	s_barrier
	s_barrier
	s_add_u32 s20, s20, 0x80
	s_add_i32 s33, s33, -1
	s_cmp_lg_u32 s33, 0
	s_cbranch_scc1 .Lp4t_loop
	ds_read_b128 v[130:133], v188 offset:0
	ds_read_b128 v[134:137], v188 offset:2048
	ds_read_b128 v[162:165], v190 offset:32768
	ds_read_b128 v[166:169], v190 offset:34816
	ds_read_b128 v[170:173], v190 offset:36864
	ds_read_b128 v[174:177], v190 offset:38912
	s_add_u32 s22, s20, 0x80
	s_add_i32 m0, s19, 0x14000
	v_lshl_add_u64 v[196:197], v[224:225], 0, s[22:23]
	global_load_lds_dwordx4 v[196:197], off
	s_add_u32 s22, s20, 0x20080
	s_add_i32 m0, s19, 0x1a000
	v_lshl_add_u64 v[198:199], v[228:229], 0, s[22:23]
	global_load_lds_dwordx4 v[198:199], off
	s_waitcnt vmcnt(4) lgkmcnt(0)
	s_barrier
	v_mfma_f32_16x16x32_f16 v[126:129], v[162:165], v[130:133], v[126:129]
	v_mfma_f32_16x16x32_f16 v[122:125], v[166:169], v[130:133], v[122:125]
	v_mfma_f32_16x16x32_f16 v[118:121], v[170:173], v[130:133], v[118:121]
	v_mfma_f32_16x16x32_f16 v[114:117], v[174:177], v[130:133], v[114:117]
	v_mfma_f32_16x16x32_f16 v[110:113], v[162:165], v[134:137], v[110:113]
	v_mfma_f32_16x16x32_f16 v[106:109], v[166:169], v[134:137], v[106:109]
	v_mfma_f32_16x16x32_f16 v[102:105], v[170:173], v[134:137], v[102:105]
	v_mfma_f32_16x16x32_f16 v[98:101], v[174:177], v[134:137], v[98:101]
	s_barrier
	s_add_u32 s22, s20, 0x40080
	s_add_i32 m0, s19, 0x1c000
	v_lshl_add_u64 v[196:197], v[228:229], 0, s[22:23]
	global_load_lds_dwordx4 v[196:197], off
	s_add_u32 s22, s20, 0x60080
	s_add_i32 m0, s19, 0x1e000
	v_lshl_add_u64 v[198:199], v[228:229], 0, s[22:23]
	global_load_lds_dwordx4 v[198:199], off
	s_waitcnt lgkmcnt(0)
	s_barrier
	s_barrier
	ds_read_b128 v[130:133], v189 offset:0
	ds_read_b128 v[134:137], v189 offset:2048
	ds_read_b128 v[162:165], v191 offset:32768
	ds_read_b128 v[166:169], v191 offset:34816
	ds_read_b128 v[170:173], v191 offset:36864
	ds_read_b128 v[174:177], v191 offset:38912
	s_add_u32 s22, s20, 0x80
	s_add_i32 m0, s19, 0x12000
	v_lshl_add_u64 v[196:197], v[220:221], 0, s[22:23]
	global_load_lds_dwordx4 v[196:197], off
	s_add_u32 s22, s20, 0x80
	s_add_i32 m0, s19, 0x16000
	v_lshl_add_u64 v[198:199], v[226:227], 0, s[22:23]
	global_load_lds_dwordx4 v[198:199], off
	s_waitcnt lgkmcnt(0)
	s_barrier
	v_mfma_f32_16x16x32_f16 v[126:129], v[162:165], v[130:133], v[126:129]
	v_mfma_f32_16x16x32_f16 v[122:125], v[166:169], v[130:133], v[122:125]
	v_mfma_f32_16x16x32_f16 v[118:121], v[170:173], v[130:133], v[118:121]
	v_mfma_f32_16x16x32_f16 v[114:117], v[174:177], v[130:133], v[114:117]
	v_mfma_f32_16x16x32_f16 v[110:113], v[162:165], v[134:137], v[110:113]
	v_mfma_f32_16x16x32_f16 v[106:109], v[166:169], v[134:137], v[106:109]
	v_mfma_f32_16x16x32_f16 v[102:105], v[170:173], v[134:137], v[102:105]
	v_mfma_f32_16x16x32_f16 v[98:101], v[174:177], v[134:137], v[98:101]
	s_barrier
	s_waitcnt vmcnt(2) lgkmcnt(0)
	s_barrier
	s_barrier
	s_add_u32 s20, s20, 0x80
	ds_read_b128 v[130:133], v192 offset:0
	ds_read_b128 v[134:137], v192 offset:2048
	ds_read_b128 v[162:165], v194 offset:32768
	ds_read_b128 v[166:169], v194 offset:34816
	ds_read_b128 v[170:173], v194 offset:36864
	ds_read_b128 v[174:177], v194 offset:38912
	s_waitcnt vmcnt(0) lgkmcnt(0)
	s_barrier
	v_mfma_f32_16x16x32_f16 v[126:129], v[162:165], v[130:133], v[126:129]
	v_mfma_f32_16x16x32_f16 v[122:125], v[166:169], v[130:133], v[122:125]
	v_mfma_f32_16x16x32_f16 v[118:121], v[170:173], v[130:133], v[118:121]
	v_mfma_f32_16x16x32_f16 v[114:117], v[174:177], v[130:133], v[114:117]
	v_mfma_f32_16x16x32_f16 v[110:113], v[162:165], v[134:137], v[110:113]
	v_mfma_f32_16x16x32_f16 v[106:109], v[166:169], v[134:137], v[106:109]
	v_mfma_f32_16x16x32_f16 v[102:105], v[170:173], v[134:137], v[102:105]
	v_mfma_f32_16x16x32_f16 v[98:101], v[174:177], v[134:137], v[98:101]
	s_barrier
	s_waitcnt lgkmcnt(0)
	s_barrier
	s_barrier
	ds_read_b128 v[130:133], v193 offset:0
	ds_read_b128 v[134:137], v193 offset:2048
	ds_read_b128 v[162:165], v195 offset:32768
	ds_read_b128 v[166:169], v195 offset:34816
	ds_read_b128 v[170:173], v195 offset:36864
	ds_read_b128 v[174:177], v195 offset:38912
	s_waitcnt lgkmcnt(0)
	s_barrier
	v_mfma_f32_16x16x32_f16 v[126:129], v[162:165], v[130:133], v[126:129]
	v_mfma_f32_16x16x32_f16 v[122:125], v[166:169], v[130:133], v[122:125]
	v_mfma_f32_16x16x32_f16 v[118:121], v[170:173], v[130:133], v[118:121]
	v_mfma_f32_16x16x32_f16 v[114:117], v[174:177], v[130:133], v[114:117]
	v_mfma_f32_16x16x32_f16 v[110:113], v[162:165], v[134:137], v[110:113]
	v_mfma_f32_16x16x32_f16 v[106:109], v[166:169], v[134:137], v[106:109]
	v_mfma_f32_16x16x32_f16 v[102:105], v[170:173], v[134:137], v[102:105]
	v_mfma_f32_16x16x32_f16 v[98:101], v[174:177], v[134:137], v[98:101]
	s_barrier
	s_waitcnt lgkmcnt(0)
	s_barrier
	s_barrier
	s_cmp_eq_u32 s29, 1
	s_cbranch_scc1 .Lp4t_skew1
	s_barrier
.Lp4t_skew1:
	s_nop 7
	s_nop 1
	v_and_b32_e32 v200, 15, v222
	v_lshrrev_b32_e32 v201, 8, v222
	v_lshl_or_b32 v200, v201, 5, v200
	v_bfe_u32 v201, v222, 6, 2
	v_bfe_u32 v202, v222, 4, 2
	v_lshlrev_b32_e32 v203, 2, v202
	v_lshl_or_b32 v203, v201, 5, v203
	s_lshl_b32 s4, s18, 7
	v_or_b32_e32 v204, s4, v203
	v_lshlrev_b32_e32 v205, 2, v204
	v_lshlrev_b32_e32 v207, 1, v204
	global_load_dwordx4 v[130:133], v205, s[10:11]
	global_load_dwordx4 v[134:137], v205, s[12:13]
	global_load_dwordx4 v[138:141], v205, s[14:15]
	global_load_dwordx4 v[142:145], v205, s[10:11] offset:64
	global_load_dwordx4 v[146:149], v205, s[12:13] offset:64
	global_load_dwordx4 v[150:153], v205, s[14:15] offset:64
	v_mul_u32_u24_e32 v206, 0x110, v200
	v_lshl_add_u32 v206, v203, 1, v206
	v_add_u32_e32 v206, 0x10000, v206
	v_cvt_pk_f16_f32 v170, v126, v127
	v_cvt_pk_f16_f32 v171, v128, v129
	v_cvt_pk_f16_f32 v172, v118, v119
	v_cvt_pk_f16_f32 v173, v120, v121
	ds_write2_b64 v206, v[170:171], v[172:173] offset1:4
	v_cvt_pk_f16_f32 v174, v110, v111
	v_cvt_pk_f16_f32 v175, v112, v113
	v_cvt_pk_f16_f32 v176, v102, v103
	v_cvt_pk_f16_f32 v177, v104, v105
	v_add_u32_e32 v178, 0x1100, v206
	ds_write2_b64 v178, v[174:175], v[176:177] offset1:4
	v_add_u32_e32 v201, 0xfffffef0, v206
	s_waitcnt lgkmcnt(0)
	s_barrier
	ds_read2_b64 v[154:157], v201 offset1:4
	ds_read2_b64 v[158:161], v201 offset0:68 offset1:72
	s_waitcnt vmcnt(0)
	v_add_u32_e32 v179, 0x1100, v201
	ds_read2_b64 v[162:165], v179 offset1:4
	ds_read2_b64 v[166:169], v179 offset0:68 offset1:72
	v_add_u32_e32 v180, 0, v200
	v_add_u32_e32 v181, s28, v180
	v_add_u32_e32 v182, -1, v180
	v_cmp_gt_u32_e32 vcc, 0x3e, v182
	v_cmp_gt_i32_e64 s[2:3], s6, v181
	v_cmp_gt_i32_e64 s[4:5], s68, v181
	v_mad_u32_u24 v183, v181, s52, v207
	s_and_b64 s[2:3], vcc, s[2:3]
	v_cndmask_b32_e64 v184, v216, v217, s[4:5]
	v_and_b32_e32 v185, v184, v181
	v_cmp_eq_u32_e32 vcc, 0, v185
	s_nop 1
	v_cndmask_b32_e64 v186, -1, 0, vcc
	v_cmp_eq_u32_e32 vcc, v185, v184
	s_nop 1
	v_cndmask_b32_e64 v188, -1, 0, vcc
	s_and_saveexec_b64 s[4:5], s[2:3]
	s_waitcnt lgkmcnt(2)
	v_pk_mul_f32 v[126:127], v[126:127], v[134:135]
	v_pk_mul_f32 v[128:129], v[128:129], v[136:137]
	v_and_b32_e32 v154, v186, v154
	v_and_b32_e32 v155, v186, v155
	v_and_b32_e32 v158, v188, v158
	v_and_b32_e32 v159, v188, v159
	v_fma_mix_f32 v126, v130, v154, v126 op_sel:[0,0,0] op_sel_hi:[0,1,0]
	v_fma_mix_f32 v127, v131, v154, v127 op_sel:[0,1,0] op_sel_hi:[0,1,0]
	v_fma_mix_f32 v128, v132, v155, v128 op_sel:[0,0,0] op_sel_hi:[0,1,0]
	v_fma_mix_f32 v129, v133, v155, v129 op_sel:[0,1,0] op_sel_hi:[0,1,0]
	v_fma_mix_f32 v126, v138, v158, v126 op_sel:[0,0,0] op_sel_hi:[0,1,0]
	v_fma_mix_f32 v127, v139, v158, v127 op_sel:[0,1,0] op_sel_hi:[0,1,0]
	v_fma_mix_f32 v128, v140, v159, v128 op_sel:[0,0,0] op_sel_hi:[0,1,0]
	v_fma_mix_f32 v129, v141, v159, v129 op_sel:[0,1,0] op_sel_hi:[0,1,0]
	v_mul_f32_e32 v190, 0xbfb8aa3b, v126
	v_mul_f32_e32 v191, 0xbfb8aa3b, v127
	v_mul_f32_e32 v192, 0xbfb8aa3b, v128
	v_mul_f32_e32 v193, 0xbfb8aa3b, v129
	v_exp_f32_e32 v190, v190
	v_exp_f32_e32 v191, v191
	v_exp_f32_e32 v192, v192
	v_exp_f32_e32 v193, v193
	v_add_f32_e32 v190, 1.0, v190
	v_add_f32_e32 v191, 1.0, v191
	v_add_f32_e32 v192, 1.0, v192
	v_add_f32_e32 v193, 1.0, v193
	v_rcp_f32_e32 v190, v190
	v_rcp_f32_e32 v191, v191
	v_rcp_f32_e32 v192, v192
	v_rcp_f32_e32 v193, v193
	s_nop 0
	v_pk_mul_f32 v[126:127], v[126:127], v[190:191]
	v_pk_mul_f32 v[128:129], v[128:129], v[192:193]
	v_pk_mul_f32 v[126:127], v[122:123], v[126:127]
	v_pk_mul_f32 v[128:129], v[124:125], v[128:129]
	v_cvt_pk_f16_f32 v126, v126, v127
	v_cvt_pk_f16_f32 v127, v128, v129
	global_store_dwordx2 v183, v[126:127], s[96:97]
	v_pk_mul_f32 v[118:119], v[118:119], v[146:147]
	v_pk_mul_f32 v[120:121], v[120:121], v[148:149]
	v_and_b32_e32 v156, v186, v156
	v_and_b32_e32 v157, v186, v157
	v_and_b32_e32 v160, v188, v160
	v_and_b32_e32 v161, v188, v161
	v_fma_mix_f32 v118, v142, v156, v118 op_sel:[0,0,0] op_sel_hi:[0,1,0]
	v_fma_mix_f32 v119, v143, v156, v119 op_sel:[0,1,0] op_sel_hi:[0,1,0]
	v_fma_mix_f32 v120, v144, v157, v120 op_sel:[0,0,0] op_sel_hi:[0,1,0]
	v_fma_mix_f32 v121, v145, v157, v121 op_sel:[0,1,0] op_sel_hi:[0,1,0]
	v_fma_mix_f32 v118, v150, v160, v118 op_sel:[0,0,0] op_sel_hi:[0,1,0]
	v_fma_mix_f32 v119, v151, v160, v119 op_sel:[0,1,0] op_sel_hi:[0,1,0]
	v_fma_mix_f32 v120, v152, v161, v120 op_sel:[0,0,0] op_sel_hi:[0,1,0]
	v_fma_mix_f32 v121, v153, v161, v121 op_sel:[0,1,0] op_sel_hi:[0,1,0]
	v_mul_f32_e32 v190, 0xbfb8aa3b, v118
	v_mul_f32_e32 v191, 0xbfb8aa3b, v119
	v_mul_f32_e32 v192, 0xbfb8aa3b, v120
	v_mul_f32_e32 v193, 0xbfb8aa3b, v121
	v_exp_f32_e32 v190, v190
	v_exp_f32_e32 v191, v191
	v_exp_f32_e32 v192, v192
	v_exp_f32_e32 v193, v193
	v_add_f32_e32 v190, 1.0, v190
	v_add_f32_e32 v191, 1.0, v191
	v_add_f32_e32 v192, 1.0, v192
	v_add_f32_e32 v193, 1.0, v193
	v_rcp_f32_e32 v190, v190
	v_rcp_f32_e32 v191, v191
	v_rcp_f32_e32 v192, v192
	v_rcp_f32_e32 v193, v193
	s_nop 0
	v_pk_mul_f32 v[118:119], v[118:119], v[190:191]
	v_pk_mul_f32 v[120:121], v[120:121], v[192:193]
	v_pk_mul_f32 v[118:119], v[114:115], v[118:119]
	v_pk_mul_f32 v[120:121], v[116:117], v[120:121]
	v_cvt_pk_f16_f32 v118, v118, v119
	v_cvt_pk_f16_f32 v119, v120, v121
	global_store_dwordx2 v183, v[118:119], s[96:97] offset:32
	s_mov_b64 exec, s[4:5]
	v_add_u32_e32 v180, 16, v200
	v_add_u32_e32 v181, s28, v180
	v_add_u32_e32 v182, -1, v180
	v_cmp_gt_u32_e32 vcc, 0x3e, v182
	v_cmp_gt_i32_e64 s[2:3], s6, v181
	v_cmp_gt_i32_e64 s[4:5], s68, v181
	v_mad_u32_u24 v183, v181, s52, v207
	s_and_b64 s[2:3], vcc, s[2:3]
	v_cndmask_b32_e64 v184, v216, v217, s[4:5]
	v_and_b32_e32 v185, v184, v181
	v_cmp_eq_u32_e32 vcc, 0, v185
	s_nop 1
	v_cndmask_b32_e64 v186, -1, 0, vcc
	v_cmp_eq_u32_e32 vcc, v185, v184
	s_nop 1
	v_cndmask_b32_e64 v188, -1, 0, vcc
	s_and_saveexec_b64 s[4:5], s[2:3]
	s_waitcnt lgkmcnt(0)
	v_pk_mul_f32 v[110:111], v[110:111], v[134:135]
	v_pk_mul_f32 v[112:113], v[112:113], v[136:137]
	v_and_b32_e32 v162, v186, v162
	v_and_b32_e32 v163, v186, v163
	v_and_b32_e32 v166, v188, v166
	v_and_b32_e32 v167, v188, v167
	v_fma_mix_f32 v110, v130, v162, v110 op_sel:[0,0,0] op_sel_hi:[0,1,0]
	v_fma_mix_f32 v111, v131, v162, v111 op_sel:[0,1,0] op_sel_hi:[0,1,0]
	v_fma_mix_f32 v112, v132, v163, v112 op_sel:[0,0,0] op_sel_hi:[0,1,0]
	v_fma_mix_f32 v113, v133, v163, v113 op_sel:[0,1,0] op_sel_hi:[0,1,0]
	v_fma_mix_f32 v110, v138, v166, v110 op_sel:[0,0,0] op_sel_hi:[0,1,0]
	v_fma_mix_f32 v111, v139, v166, v111 op_sel:[0,1,0] op_sel_hi:[0,1,0]
	v_fma_mix_f32 v112, v140, v167, v112 op_sel:[0,0,0] op_sel_hi:[0,1,0]
	v_fma_mix_f32 v113, v141, v167, v113 op_sel:[0,1,0] op_sel_hi:[0,1,0]
	v_mul_f32_e32 v190, 0xbfb8aa3b, v110
	v_mul_f32_e32 v191, 0xbfb8aa3b, v111
	v_mul_f32_e32 v192, 0xbfb8aa3b, v112
	v_mul_f32_e32 v193, 0xbfb8aa3b, v113
	v_exp_f32_e32 v190, v190
	v_exp_f32_e32 v191, v191
	v_exp_f32_e32 v192, v192
	v_exp_f32_e32 v193, v193
	v_add_f32_e32 v190, 1.0, v190
	v_add_f32_e32 v191, 1.0, v191
	v_add_f32_e32 v192, 1.0, v192
	v_add_f32_e32 v193, 1.0, v193
	v_rcp_f32_e32 v190, v190
	v_rcp_f32_e32 v191, v191
	v_rcp_f32_e32 v192, v192
	v_rcp_f32_e32 v193, v193
	s_nop 0
	v_pk_mul_f32 v[110:111], v[110:111], v[190:191]
	v_pk_mul_f32 v[112:113], v[112:113], v[192:193]
	v_pk_mul_f32 v[110:111], v[106:107], v[110:111]
	v_pk_mul_f32 v[112:113], v[108:109], v[112:113]
	v_cvt_pk_f16_f32 v110, v110, v111
	v_cvt_pk_f16_f32 v111, v112, v113
	global_store_dwordx2 v183, v[110:111], s[96:97]
	v_pk_mul_f32 v[102:103], v[102:103], v[146:147]
	v_pk_mul_f32 v[104:105], v[104:105], v[148:149]
	v_and_b32_e32 v164, v186, v164
	v_and_b32_e32 v165, v186, v165
	v_and_b32_e32 v168, v188, v168
	v_and_b32_e32 v169, v188, v169
	v_fma_mix_f32 v102, v142, v164, v102 op_sel:[0,0,0] op_sel_hi:[0,1,0]
	v_fma_mix_f32 v103, v143, v164, v103 op_sel:[0,1,0] op_sel_hi:[0,1,0]
	v_fma_mix_f32 v104, v144, v165, v104 op_sel:[0,0,0] op_sel_hi:[0,1,0]
	v_fma_mix_f32 v105, v145, v165, v105 op_sel:[0,1,0] op_sel_hi:[0,1,0]
	v_fma_mix_f32 v102, v150, v168, v102 op_sel:[0,0,0] op_sel_hi:[0,1,0]
	v_fma_mix_f32 v103, v151, v168, v103 op_sel:[0,1,0] op_sel_hi:[0,1,0]
	v_fma_mix_f32 v104, v152, v169, v104 op_sel:[0,0,0] op_sel_hi:[0,1,0]
	v_fma_mix_f32 v105, v153, v169, v105 op_sel:[0,1,0] op_sel_hi:[0,1,0]
	v_mul_f32_e32 v190, 0xbfb8aa3b, v102
	v_mul_f32_e32 v191, 0xbfb8aa3b, v103
	v_mul_f32_e32 v192, 0xbfb8aa3b, v104
	v_mul_f32_e32 v193, 0xbfb8aa3b, v105
	v_exp_f32_e32 v190, v190
	v_exp_f32_e32 v191, v191
	v_exp_f32_e32 v192, v192
	v_exp_f32_e32 v193, v193
	v_add_f32_e32 v190, 1.0, v190
	v_add_f32_e32 v191, 1.0, v191
	v_add_f32_e32 v192, 1.0, v192
	v_add_f32_e32 v193, 1.0, v193
	v_rcp_f32_e32 v190, v190
	v_rcp_f32_e32 v191, v191
	v_rcp_f32_e32 v192, v192
	v_rcp_f32_e32 v193, v193
	s_nop 0
	v_pk_mul_f32 v[102:103], v[102:103], v[190:191]
	v_pk_mul_f32 v[104:105], v[104:105], v[192:193]
	v_pk_mul_f32 v[102:103], v[98:99], v[102:103]
	v_pk_mul_f32 v[104:105], v[100:101], v[104:105]
	v_cvt_pk_f16_f32 v102, v102, v103
	v_cvt_pk_f16_f32 v103, v104, v105
	global_store_dwordx2 v183, v[102:103], s[96:97] offset:32
	s_mov_b64 exec, s[4:5]
	s_waitcnt vmcnt(0)
